# hoisted loop-invariant norm-gain loads out of the four RMSNorm row loops and the diff-attention epilogue (compiler had serialized them store-load-wait); plus earlier barrier/priority tweaks
# speedup vs baseline: 1.0123x; 1.0123x over previous
; __device__ __forceinline__ unsigned cvtpk(float lo, float hi) { unsigned r; asm volatile("v_cvt_pk_bf16_f32 %0, %1, %2" : "=v"(r) : "v"(lo), "v"(hi)); return r; }
; __device__ __forceinline__ void norm_rows(const float* xp, const float* xs, const float* g, bf16_t* xn) {
;     const int lane = threadIdx.x & 63, gw = blockIdx.x * 8 + (threadIdx.x >> 6), nw = gridDim.x * 8;
;     for (int row = gw; row < MT; row += nw) {
;         const float* xr = (row < MP) ? xp + (size_t)row * DM : xs + (size_t)(row - MP) * DM;
;         f32x4 v[8]; float ss = 0.f;
; #pragma unroll
;         for (int i = 0; i < 8; ++i) { v[i] = *(const f32x4*)(xr + (i * 64 + lane) * 4); ss += v[i][0] * v[i][0] + v[i][1] * v[i][1] + v[i][2] * v[i][2] + v[i][3] * v[i][3]; }
;         ss = wave_sum(ss); const float rs = rsqrtf(ss * (1.0f / DM) + EPS);
; #pragma unroll
;         for (int i = 0; i < 8; ++i) { const f32x4 gg = *(const f32x4*)(g + (i * 64 + lane) * 4);
;             u32x2 w; w.x = cvtpk(v[i][0] * rs * gg[0], v[i][1] * rs * gg[1]); w.y = cvtpk(v[i][2] * rs * gg[2], v[i][3] * rs * gg[3]);
;             *(u32x2*)(xn + (size_t)row * DM + (i * 64 + lane) * 4) = w; }
.LBB0_32:
	s_or_b64 exec, exec, s[6:7]
	v_lshrrev_b32_e32 v2, 6, v146
	v_lshl_add_u32 v20, s86, 3, v2
	s_mov_b32 s2, 0x8200
	v_cmp_gt_i32_e32 vcc, s2, v20
	s_and_saveexec_b64 s[6:7], vcc
	s_cbranch_execz .LBB0_37
	s_waitcnt lgkmcnt(0)
	v_mbcnt_lo_u32_b32 v3, -1, 0
	v_mbcnt_hi_u32_b32 v3, -1, v3
	v_and_b32_e32 v5, 64, v3
	v_add_u32_e32 v5, 64, v5
	v_xor_b32_e32 v7, 32, v3
	v_cmp_lt_i32_e32 vcc, v7, v5
	v_and_b32_e32 v2, 0xfc, v1
	v_mov_b32_e32 v23, 0
	v_cndmask_b32_e32 v7, v3, v7, vcc
	v_lshlrev_b32_e32 v19, 2, v7
	v_xor_b32_e32 v7, 16, v3
	v_cmp_lt_i32_e32 vcc, v7, v5
	v_lshlrev_b32_e32 v22, 2, v2
	v_or_b32_e32 v4, 0x400, v2
	v_cndmask_b32_e32 v7, v3, v7, vcc
	v_lshlrev_b32_e32 v52, 2, v7
	v_xor_b32_e32 v7, 8, v3
	v_cmp_lt_i32_e32 vcc, v7, v5
	v_lshl_add_u64 v[24:25], s[48:49], 0, v[22:23]
	v_or_b32_e32 v6, 0x500, v2
	v_cndmask_b32_e32 v7, v3, v7, vcc
	v_lshlrev_b32_e32 v53, 2, v7
	v_xor_b32_e32 v7, 4, v3
	v_cmp_lt_i32_e32 vcc, v7, v5
	v_lshlrev_b32_e32 v22, 2, v4
	v_or_b32_e32 v8, 0x600, v2
	v_cndmask_b32_e32 v7, v3, v7, vcc
	v_lshlrev_b32_e32 v54, 2, v7
	v_xor_b32_e32 v7, 2, v3
	v_cmp_lt_i32_e32 vcc, v7, v5
	v_lshl_add_u64 v[26:27], s[48:49], 0, v[22:23]
	v_lshlrev_b32_e32 v22, 2, v6
	v_cndmask_b32_e32 v7, v3, v7, vcc
	v_or_b32_e32 v10, 0x700, v2
	v_lshl_add_u64 v[28:29], s[48:49], 0, v[22:23]
	v_lshlrev_b32_e32 v22, 2, v8
	v_lshlrev_b32_e32 v55, 2, v7
	v_xor_b32_e32 v7, 1, v3
	s_lshl_b32 s8, s88, 3
	v_lshl_add_u64 v[30:31], s[48:49], 0, v[22:23]
	v_lshlrev_b32_e32 v22, 2, v10
	v_cmp_lt_i32_e32 vcc, v7, v5
	v_ashrrev_i32_e32 v21, 31, v20
	v_lshl_add_u64 v[32:33], s[48:49], 0, v[22:23]
	v_cndmask_b32_e32 v3, v3, v7, vcc
	v_lshlrev_b32_e32 v22, 1, v2
	s_ashr_i32 s9, s8, 31
	v_lshlrev_b64 v[12:13], 13, v[20:21]
	v_lshlrev_b32_e32 v56, 2, v3
	v_lshl_add_u64 v[34:35], s[84:85], 0, v[22:23]
	v_lshl_add_u64 v[36:37], s[36:37], 0, v[12:13]
	s_lshl_b64 s[10:11], s[8:9], 13
	s_mov_b64 s[12:13], 0
	s_movk_i32 s2, 0x7fff
	v_lshlrev_b32_e32 v38, 2, v2
	v_lshlrev_b32_e32 v40, 2, v4
	v_lshlrev_b32_e32 v42, 2, v6
	v_lshlrev_b32_e32 v44, 2, v8
	v_lshlrev_b32_e32 v46, 2, v10
	v_mov_b32_e32 v57, 0x358637bd
	s_mov_b32 s3, 0x800000
	s_mov_b32 s5, 0x81ff
	v_mov_b32_e32 v39, v23
	v_mov_b32_e32 v41, v23
	v_mov_b32_e32 v43, v23
	v_mov_b32_e32 v45, v23
	v_mov_b32_e32 v47, v23
	global_load_dwordx4 v[96:99], v[24:25], off
	global_load_dwordx4 v[100:103], v[24:25], off offset:1024
	global_load_dwordx4 v[104:107], v[24:25], off offset:2048
	global_load_dwordx4 v[108:111], v[24:25], off offset:3072
	global_load_dwordx4 v[112:115], v[26:27], off
	global_load_dwordx4 v[116:119], v[28:29], off
	global_load_dwordx4 v[120:123], v[30:31], off
	global_load_dwordx4 v[124:127], v[32:33], off
	s_branch .LBB0_35
; __device__ __forceinline__ unsigned cvtpk(float lo, float hi) { unsigned r; asm volatile("v_cvt_pk_bf16_f32 %0, %1, %2" : "=v"(r) : "v"(lo), "v"(hi)); return r; }
; __device__ __forceinline__ void norm_rows(const float* xp, const float* xs, const float* g, bf16_t* xn) {
;     ...
;     for (int row = gw; row < MT; row += nw) {
;         const float* xr = (row < MP) ? xp + (size_t)row * DM : xs + (size_t)(row - MP) * DM;
;         f32x4 v[8]; float ss = 0.f;
; #pragma unroll
;         for (int i = 0; i < 8; ++i) { v[i] = *(const f32x4*)(xr + (i * 64 + lane) * 4); ss += v[i][0] * v[i][0] + v[i][1] * v[i][1] + v[i][2] * v[i][2] + v[i][3] * v[i][3]; }
;         ss = wave_sum(ss); const float rs = rsqrtf(ss * (1.0f / DM) + EPS);
; #pragma unroll
;         for (int i = 0; i < 8; ++i) { const f32x4 gg = *(const f32x4*)(g + (i * 64 + lane) * 4);
;             u32x2 w; w.x = cvtpk(v[i][0] * rs * gg[0], v[i][1] * rs * gg[1]); w.y = cvtpk(v[i][2] * rs * gg[2], v[i][3] * rs * gg[3]);
;             *(u32x2*)(xn + (size_t)row * DM + (i * 64 + lane) * 4) = w; }
;     }
.LBB0_34:
	s_or_b64 exec, exec, s[16:17]
	v_lshl_add_u64 v[2:3], v[50:51], 0, v[40:41]
	v_lshl_add_u64 v[4:5], v[50:51], 0, v[42:43]
	global_load_dwordx4 v[14:17], v[2:3], off
	global_load_dwordx4 v[6:9], v[4:5], off
	v_lshl_add_u64 v[2:3], v[50:51], 0, v[44:45]
	v_lshl_add_u64 v[4:5], v[50:51], 0, v[46:47]
	v_lshl_add_u64 v[50:51], v[50:51], 0, v[38:39]
	global_load_dwordx4 v[10:13], v[2:3], off
	s_nop 0
	global_load_dwordx4 v[2:5], v[4:5], off
	s_nop 0
	global_load_dwordx4 v[58:61], v[50:51], off
	global_load_dwordx4 v[62:65], v[50:51], off offset:1024
	global_load_dwordx4 v[66:69], v[50:51], off offset:2048
	global_load_dwordx4 v[70:73], v[50:51], off offset:3072
	v_lshlrev_b64 v[48:49], 12, v[48:49]
	v_lshl_add_u64 v[20:21], v[20:21], 0, s[8:9]
	v_lshl_add_u64 v[36:37], v[36:37], 0, s[10:11]
	s_waitcnt vmcnt(7)
	v_mov_b32_e32 v78, v15
	s_waitcnt vmcnt(6)
	v_mov_b32_e32 v79, v7
	s_waitcnt vmcnt(3)
	v_mul_f32_e32 v22, v59, v59
	s_waitcnt vmcnt(2)
	v_mul_f32_e32 v92, v63, v63
	s_waitcnt vmcnt(1)
	v_mul_f32_e32 v93, v67, v67
	v_fmac_f32_e32 v22, v58, v58
	v_fmac_f32_e32 v92, v62, v62
	s_waitcnt vmcnt(0)
	v_mul_f32_e32 v94, v71, v71
	v_fmac_f32_e32 v93, v66, v66
	v_fmac_f32_e32 v22, v60, v60
	v_fmac_f32_e32 v92, v64, v64
	v_mov_b32_e32 v50, v14
	v_mov_b32_e32 v51, v6
	v_pk_mul_f32 v[78:79], v[78:79], v[78:79]
	v_fmac_f32_e32 v94, v70, v70
	v_fmac_f32_e32 v93, v68, v68
	v_fmac_f32_e32 v22, v61, v61
	v_fmac_f32_e32 v92, v65, v65
	v_mov_b32_e32 v82, v11
	v_mov_b32_e32 v83, v3
	v_mov_b32_e32 v84, v16
	v_mov_b32_e32 v85, v8
	v_pk_fma_f32 v[50:51], v[50:51], v[50:51], v[78:79]
	v_fmac_f32_e32 v94, v72, v72
	v_fmac_f32_e32 v93, v69, v69
	v_add_f32_e32 v22, v22, v92
	v_mov_b32_e32 v80, v10
	v_mov_b32_e32 v81, v2
	v_mov_b32_e32 v88, v17
	v_mov_b32_e32 v89, v9
	v_pk_mul_f32 v[82:83], v[82:83], v[82:83]
	v_pk_fma_f32 v[50:51], v[84:85], v[84:85], v[50:51]
	v_fmac_f32_e32 v94, v73, v73
	v_add_f32_e32 v22, v22, v93
	v_mov_b32_e32 v86, v12
	v_mov_b32_e32 v87, v4
	v_pk_fma_f32 v[78:79], v[80:81], v[80:81], v[82:83]
	v_pk_fma_f32 v[50:51], v[88:89], v[88:89], v[50:51]
	v_add_f32_e32 v22, v22, v94
	v_mov_b32_e32 v90, v13
	v_mov_b32_e32 v91, v5
	v_pk_fma_f32 v[78:79], v[86:87], v[86:87], v[78:79]
	v_add_f32_e32 v22, v22, v50
	v_pk_fma_f32 v[78:79], v[90:91], v[90:91], v[78:79]
	v_add_f32_e32 v22, v22, v51
	v_add_f32_e32 v22, v22, v78
	v_add_f32_e32 v22, v22, v79
	ds_bpermute_b32 v50, v19, v22
	v_lshl_add_u64 v[78:79], v[34:35], 0, v[48:49]
	s_waitcnt lgkmcnt(0)
	v_add_f32_e32 v22, v22, v50
	ds_bpermute_b32 v50, v52, v22
	s_waitcnt lgkmcnt(0)
	v_add_f32_e32 v22, v22, v50
	ds_bpermute_b32 v50, v53, v22
	s_waitcnt lgkmcnt(0)
	v_add_f32_e32 v22, v22, v50
	ds_bpermute_b32 v50, v54, v22
	s_waitcnt lgkmcnt(0)
	v_add_f32_e32 v22, v22, v50
	ds_bpermute_b32 v50, v55, v22
	s_waitcnt lgkmcnt(0)
	v_add_f32_e32 v22, v22, v50
	ds_bpermute_b32 v50, v56, v22
	s_waitcnt lgkmcnt(0)
	v_add_f32_e32 v22, v22, v50
	v_fmamk_f32 v22, v22, 0x3a000000, v57
	v_mul_f32_e32 v50, 0x4b800000, v22
	v_cmp_gt_f32_e32 vcc, s3, v22
	s_nop 1
	v_cndmask_b32_e32 v22, v22, v50, vcc
	v_rsq_f32_e32 v22, v22
	s_nop 0
	v_mul_f32_e32 v48, 0x45800000, v22
	v_cndmask_b32_e32 v22, v22, v48, vcc
	v_mul_f32_e32 v48, v58, v22
	v_mul_f32_e32 v49, v59, v22
	v_mul_f32_e32 v50, v60, v22
	v_mul_f32_e32 v51, v61, v22
	s_waitcnt vmcnt(0)
	v_mul_f32_e32 v48, v96, v48
	v_mul_f32_e32 v49, v97, v49
	v_mul_f32_e32 v50, v98, v50
	v_mul_f32_e32 v51, v99, v51
	v_cvt_pk_bf16_f32 v48, v48, v49
	v_cvt_pk_bf16_f32 v49, v50, v51
	global_store_dwordx2 v[78:79], v[48:49], off
	v_mul_f32_e32 v58, v62, v22
	v_mul_f32_e32 v59, v63, v22
	v_mul_f32_e32 v60, v64, v22
	v_mul_f32_e32 v61, v65, v22
	v_mul_f32_e32 v14, v14, v22
	v_mul_f32_e32 v15, v15, v22
	v_mul_f32_e32 v16, v16, v22
	v_mul_f32_e32 v17, v17, v22
	v_mul_f32_e32 v6, v6, v22
	v_mul_f32_e32 v7, v7, v22
	v_mul_f32_e32 v8, v8, v22
	v_mul_f32_e32 v9, v9, v22
	v_mul_f32_e32 v10, v10, v22
	v_mul_f32_e32 v11, v11, v22
	v_mul_f32_e32 v12, v12, v22
	v_mul_f32_e32 v13, v13, v22
	v_cmp_lt_i32_e32 vcc, s5, v20
	v_mul_f32_e32 v2, v2, v22
	v_mul_f32_e32 v3, v3, v22
	s_or_b64 s[12:13], vcc, s[12:13]
	v_mul_f32_e32 v4, v4, v22
	v_mul_f32_e32 v5, v5, v22
	v_mul_f32_e32 v48, v100, v58
	v_mul_f32_e32 v49, v101, v59
	v_mul_f32_e32 v50, v102, v60
	v_mul_f32_e32 v51, v103, v61
	v_cvt_pk_bf16_f32 v48, v48, v49
	v_cvt_pk_bf16_f32 v49, v50, v51
	global_store_dwordx2 v[78:79], v[48:49], off offset:512
	v_mul_f32_e32 v58, v66, v22
	v_mul_f32_e32 v59, v67, v22
	v_mul_f32_e32 v60, v68, v22
	v_mul_f32_e32 v61, v69, v22
	v_mul_f32_e32 v48, v104, v58
	v_mul_f32_e32 v49, v105, v59
	v_mul_f32_e32 v50, v106, v60
	v_mul_f32_e32 v51, v107, v61
	v_cvt_pk_bf16_f32 v48, v48, v49
	v_cvt_pk_bf16_f32 v49, v50, v51
	global_store_dwordx2 v[78:79], v[48:49], off offset:1024
	v_mul_f32_e32 v58, v70, v22
	v_mul_f32_e32 v59, v71, v22
	v_mul_f32_e32 v60, v72, v22
	v_mul_f32_e32 v61, v73, v22
	v_mul_f32_e32 v48, v58, v108
	v_mul_f32_e32 v49, v59, v109
	v_mul_f32_e32 v50, v60, v110
	v_mul_f32_e32 v51, v61, v111
	v_cvt_pk_bf16_f32 v48, v48, v49
	v_cvt_pk_bf16_f32 v49, v50, v51
	global_store_dwordx2 v[78:79], v[48:49], off offset:1536
	v_mul_f32_e32 v14, v14, v112
	v_mul_f32_e32 v15, v15, v113
	v_mul_f32_e32 v16, v16, v114
	v_mul_f32_e32 v17, v17, v115
	v_cvt_pk_bf16_f32 v14, v14, v15
	v_cvt_pk_bf16_f32 v15, v16, v17
	global_store_dwordx2 v[78:79], v[14:15], off offset:2048
	v_mul_f32_e32 v6, v6, v116
	v_mul_f32_e32 v7, v7, v117
	v_mul_f32_e32 v8, v8, v118
	v_mul_f32_e32 v9, v9, v119
	v_cvt_pk_bf16_f32 v6, v6, v7
	v_cvt_pk_bf16_f32 v7, v8, v9
	global_store_dwordx2 v[78:79], v[6:7], off offset:2560
	v_mul_f32_e32 v6, v10, v120
	v_mul_f32_e32 v7, v11, v121
	v_mul_f32_e32 v8, v12, v122
	v_mul_f32_e32 v9, v13, v123
	v_cvt_pk_bf16_f32 v6, v6, v7
	v_cvt_pk_bf16_f32 v7, v8, v9
	global_store_dwordx2 v[78:79], v[6:7], off offset:3072
	v_mul_f32_e32 v2, v2, v124
	v_mul_f32_e32 v3, v3, v125
	v_mul_f32_e32 v4, v4, v126
	v_mul_f32_e32 v5, v5, v127
	v_cvt_pk_bf16_f32 v2, v2, v3
	v_cvt_pk_bf16_f32 v3, v4, v5
	global_store_dwordx2 v[78:79], v[2:3], off offset:3584
	s_andn2_b64 exec, exec, s[12:13]
	s_cbranch_execz .LBB0_37

; __device__ __forceinline__ void norm_rows_mixed(const bf16_t* xb, const float* xs, const float* g, bf16_t* xn) {
;     const int lane = threadIdx.x & 63, gw = blockIdx.x * 8 + (threadIdx.x >> 6), nw = gridDim.x * 8;
;     for (int row = gw; row < MP; row += nw) {
;         u32x2 w[8]; float ss = 0.f;
; #pragma unroll
;         for (int i = 0; i < 8; ++i) w[i] = *(const u32x2*)(xb + (size_t)row * DM + (i * 64 + lane) * 4);
; #pragma unroll
;         for (int i = 0; i < 8; ++i) { const float a0 = __uint_as_float(w[i].x << 16), a1 = __uint_as_float(w[i].x & 0xffff0000u), a2 = __uint_as_float(w[i].y << 16), a3 = __uint_as_float(w[i].y & 0xffff0000u);
;             ss += a0 * a0 + a1 * a1 + a2 * a2 + a3 * a3; }
;         ss = wave_sum(ss); const float rs = rsqrtf(ss * (1.0f / DM) + EPS);
; #pragma unroll
;         for (int i = 0; i < 8; ++i) { const f32x4 gg = *(const f32x4*)(g + (i * 64 + lane) * 4);
.LBB0_306:
	s_cmp_lt_i32 s78, 4
	s_cselect_b64 s[2:3], -1, 0
	s_and_b64 s[0:1], s[2:3], s[0:1]
	s_andn2_b64 vcc, exec, s[0:1]
	v_lshrrev_b32_e32 v213, 6, v146
	v_lshlrev_b32_e32 v150, 4, v148
	s_cbranch_vccnz .LBB0_318
	s_waitcnt lgkmcnt(0)
	v_mov_b32_e32 v5, 0
	v_or_b32_e32 v4, 0x1000, v150
	v_lshl_add_u64 v[8:9], s[56:57], 0, v[4:5]
	v_or_b32_e32 v4, 0x1400, v150
	v_lshl_add_u64 v[10:11], s[56:57], 0, v[4:5]
	v_or_b32_e32 v4, 0x1800, v150
	v_lshl_add_u32 v2, s86, 3, v213
	s_mov_b32 s2, 0x8000
	v_mov_b32_e32 v151, v5
	v_lshl_add_u64 v[12:13], s[56:57], 0, v[4:5]
	v_or_b32_e32 v4, 0x1c00, v150
	s_lshl_b32 s4, s88, 3
	v_cmp_gt_i32_e32 vcc, s2, v2
	v_lshl_add_u64 v[6:7], s[56:57], 0, v[150:151]
	v_lshl_add_u64 v[14:15], s[56:57], 0, v[4:5]
	v_ashrrev_i32_e32 v3, 31, v2
	s_and_saveexec_b64 s[6:7], vcc
	s_cbranch_execz .LBB0_310
	v_mbcnt_lo_u32_b32 v4, -1, 0
	v_mbcnt_hi_u32_b32 v4, -1, v4
	v_and_b32_e32 v16, 64, v4
	v_add_u32_e32 v16, 64, v16
	v_xor_b32_e32 v17, 32, v4
	v_cmp_lt_i32_e32 vcc, v17, v16
	v_lshlrev_b64 v[18:19], 12, v[2:3]
	s_ashr_i32 s5, s4, 31
	v_cndmask_b32_e32 v17, v4, v17, vcc
	v_lshlrev_b32_e32 v20, 2, v17
	v_xor_b32_e32 v17, 16, v4
	v_cmp_lt_i32_e32 vcc, v17, v16
	s_lshl_b64 s[8:9], s[4:5], 12
	s_mov_b64 s[10:11], 0
	v_cndmask_b32_e32 v17, v4, v17, vcc
	v_lshlrev_b32_e32 v21, 2, v17
	v_xor_b32_e32 v17, 8, v4
	v_cmp_lt_i32_e32 vcc, v17, v16
	v_mov_b32_e32 v26, 0x358637bd
	s_mov_b32 s2, 0x800000
	v_cndmask_b32_e32 v17, v4, v17, vcc
	v_lshlrev_b32_e32 v22, 2, v17
	v_xor_b32_e32 v17, 4, v4
	v_cmp_lt_i32_e32 vcc, v17, v16
	s_mov_b32 s3, 0x5d85000
	s_movk_i32 s5, 0x7fff
	v_cndmask_b32_e32 v17, v4, v17, vcc
	v_lshlrev_b32_e32 v23, 2, v17
	v_xor_b32_e32 v17, 2, v4
	v_cmp_lt_i32_e32 vcc, v17, v16
	v_mov_b32_e32 v27, v2
	s_nop 0
	v_cndmask_b32_e32 v17, v4, v17, vcc
	v_lshlrev_b32_e32 v24, 2, v17
	v_xor_b32_e32 v17, 1, v4
	v_cmp_lt_i32_e32 vcc, v17, v16
	s_nop 1
	v_cndmask_b32_e32 v4, v4, v17, vcc
	v_lshlrev_b32_e32 v25, 2, v4
	v_lshlrev_b32_e32 v4, 3, v148
	v_lshl_add_u64 v[16:17], s[76:77], 0, v[18:19]
	v_lshl_add_u64 v[18:19], s[74:75], 0, v[18:19]
	global_load_dwordx4 v[96:99], v[6:7], off
	global_load_dwordx4 v[100:103], v[6:7], off offset:1024
	global_load_dwordx4 v[104:107], v[6:7], off offset:2048
	global_load_dwordx4 v[108:111], v[6:7], off offset:3072
	global_load_dwordx4 v[112:115], v[8:9], off
	global_load_dwordx4 v[116:119], v[10:11], off
	global_load_dwordx4 v[120:123], v[12:13], off
	global_load_dwordx4 v[124:127], v[14:15], off
; __device__ __forceinline__ unsigned cvtpk(float lo, float hi) { unsigned r; asm volatile("v_cvt_pk_bf16_f32 %0, %1, %2" : "=v"(r) : "v"(lo), "v"(hi)); return r; }
; __device__ __forceinline__ void norm_rows_mixed(const bf16_t* xb, const float* xs, const float* g, bf16_t* xn) {
;     ...
;     for (int row = gw; row < MP; row += nw) {
;         u32x2 w[8]; float ss = 0.f;
; #pragma unroll
;         for (int i = 0; i < 8; ++i) w[i] = *(const u32x2*)(xb + (size_t)row * DM + (i * 64 + lane) * 4);
; #pragma unroll
;         for (int i = 0; i < 8; ++i) { const float a0 = __uint_as_float(w[i].x << 16), a1 = __uint_as_float(w[i].x & 0xffff0000u), a2 = __uint_as_float(w[i].y << 16), a3 = __uint_as_float(w[i].y & 0xffff0000u);
;             ss += a0 * a0 + a1 * a1 + a2 * a2 + a3 * a3; }
;         ss = wave_sum(ss); const float rs = rsqrtf(ss * (1.0f / DM) + EPS);
; #pragma unroll
;         for (int i = 0; i < 8; ++i) { const f32x4 gg = *(const f32x4*)(g + (i * 64 + lane) * 4);
;             const float a0 = __uint_as_float(w[i].x << 16), a1 = __uint_as_float(w[i].x & 0xffff0000u), a2 = __uint_as_float(w[i].y << 16), a3 = __uint_as_float(w[i].y & 0xffff0000u);
;             u32x2 o; o.x = cvtpk(a0 * rs * gg[0], a1 * rs * gg[1]); o.y = cvtpk(a2 * rs * gg[2], a3 * rs * gg[3]);
;             *(u32x2*)(xn + (size_t)row * DM + (i * 64 + lane) * 4) = o; }
.LBB0_309:
	v_lshl_add_u64 v[32:33], v[18:19], 0, v[4:5]
	global_load_dwordx2 v[36:37], v[32:33], off
	global_load_dwordx2 v[38:39], v[32:33], off offset:512
	global_load_dwordx2 v[40:41], v[32:33], off offset:1024
	global_load_dwordx2 v[42:43], v[32:33], off offset:1536
	global_load_dwordx2 v[44:45], v[32:33], off offset:2560
	global_load_dwordx2 v[46:47], v[32:33], off offset:2048
	global_load_dwordx2 v[48:49], v[32:33], off offset:3584
	s_nop 0
	global_load_dwordx2 v[32:33], v[32:33], off offset:3072
	v_lshl_add_u64 v[34:35], v[16:17], 0, v[4:5]
	v_add_co_u32_e32 v34, vcc, s3, v34
	v_add_u32_e32 v27, s4, v27
	s_nop 0
	v_addc_co_u32_e32 v35, vcc, 0, v35, vcc
	v_lshl_add_u64 v[16:17], v[16:17], 0, s[8:9]
	v_lshl_add_u64 v[18:19], v[18:19], 0, s[8:9]
	s_waitcnt vmcnt(0)
	v_and_b32_e32 v55, 0xffff0000, v36
	v_and_b32_e32 v59, 0xffff0000, v38
	v_lshlrev_b32_e32 v54, 16, v36
	v_lshlrev_b32_e32 v58, 16, v38
	v_and_b32_e32 v63, 0xffff0000, v40
	v_mul_f32_e32 v70, v55, v55
	v_mul_f32_e32 v71, v59, v59
	v_lshlrev_b32_e32 v56, 16, v37
	v_lshlrev_b32_e32 v60, 16, v39
	v_lshlrev_b32_e32 v62, 16, v40
	v_and_b32_e32 v67, 0xffff0000, v42
	v_mul_f32_e32 v72, v63, v63
	v_fmac_f32_e32 v70, v54, v54
	v_fmac_f32_e32 v71, v58, v58
	v_and_b32_e32 v57, 0xffff0000, v37
	v_and_b32_e32 v61, 0xffff0000, v39
	v_lshlrev_b32_e32 v64, 16, v41
	v_lshlrev_b32_e32 v66, 16, v42
	v_and_b32_e32 v39, 0xffff0000, v44
	v_and_b32_e32 v38, 0xffff0000, v46
	v_mul_f32_e32 v73, v67, v67
	v_fmac_f32_e32 v72, v62, v62
	v_fmac_f32_e32 v70, v56, v56
	v_fmac_f32_e32 v71, v60, v60
	v_and_b32_e32 v65, 0xffff0000, v41
	v_lshlrev_b32_e32 v68, 16, v43
	v_and_b32_e32 v69, 0xffff0000, v43
	v_lshlrev_b32_e32 v37, 16, v44
	v_lshlrev_b32_e32 v36, 16, v46
	v_lshlrev_b32_e32 v41, 16, v45
	v_lshlrev_b32_e32 v40, 16, v47
	v_and_b32_e32 v43, 0xffff0000, v45
	v_and_b32_e32 v42, 0xffff0000, v47
	v_lshlrev_b32_e32 v45, 16, v48
	v_lshlrev_b32_e32 v44, 16, v32
	v_and_b32_e32 v47, 0xffff0000, v48
	v_and_b32_e32 v46, 0xffff0000, v32
	v_lshlrev_b32_e32 v50, 16, v33
	v_and_b32_e32 v48, 0xffff0000, v33
	v_pk_mul_f32 v[32:33], v[38:39], v[38:39]
	v_fmac_f32_e32 v73, v66, v66
	v_fmac_f32_e32 v72, v64, v64
	v_fmac_f32_e32 v70, v57, v57
	v_fmac_f32_e32 v71, v61, v61
	v_pk_fma_f32 v[32:33], v[36:37], v[36:37], v[32:33]
	v_fmac_f32_e32 v73, v68, v68
	v_fmac_f32_e32 v72, v65, v65
	v_add_f32_e32 v70, v70, v71
	v_pk_mul_f32 v[52:53], v[46:47], v[46:47]
	v_pk_fma_f32 v[32:33], v[40:41], v[40:41], v[32:33]
	v_fmac_f32_e32 v73, v69, v69
	v_add_f32_e32 v70, v70, v72
	v_lshlrev_b32_e32 v51, 16, v49
	v_pk_fma_f32 v[52:53], v[44:45], v[44:45], v[52:53]
	v_pk_fma_f32 v[32:33], v[42:43], v[42:43], v[32:33]
	v_add_f32_e32 v70, v70, v73
	v_and_b32_e32 v49, 0xffff0000, v49
	v_pk_fma_f32 v[52:53], v[50:51], v[50:51], v[52:53]
	v_add_f32_e32 v32, v70, v32
	v_pk_fma_f32 v[52:53], v[48:49], v[48:49], v[52:53]
	v_add_f32_e32 v32, v32, v33
	v_add_f32_e32 v32, v32, v52
	v_add_f32_e32 v32, v32, v53
	ds_bpermute_b32 v33, v20, v32
	s_waitcnt lgkmcnt(0)
	v_add_f32_e32 v32, v32, v33
	ds_bpermute_b32 v33, v21, v32
	s_waitcnt lgkmcnt(0)
	v_add_f32_e32 v32, v32, v33
	ds_bpermute_b32 v33, v22, v32
	s_waitcnt lgkmcnt(0)
	v_add_f32_e32 v32, v32, v33
	ds_bpermute_b32 v33, v23, v32
	s_waitcnt lgkmcnt(0)
	v_add_f32_e32 v32, v32, v33
	ds_bpermute_b32 v33, v24, v32
	s_waitcnt lgkmcnt(0)
	v_add_f32_e32 v32, v32, v33
	ds_bpermute_b32 v33, v25, v32
	s_waitcnt lgkmcnt(0)
	v_add_f32_e32 v32, v32, v33
	v_fmamk_f32 v32, v32, 0x3a000000, v26
	v_mul_f32_e32 v33, 0x4b800000, v32
	v_cmp_gt_f32_e32 vcc, s2, v32
	s_nop 1
	v_cndmask_b32_e32 v32, v32, v33, vcc
	v_rsq_f32_e32 v32, v32
	s_nop 0
	v_mul_f32_e32 v33, 0x45800000, v32
	v_cndmask_b32_e32 v32, v32, v33, vcc
	v_mul_f32_e32 v33, v32, v54
	v_mul_f32_e32 v52, v32, v55
	v_mul_f32_e32 v53, v32, v56
	v_mul_f32_e32 v54, v32, v57
	v_mul_f32_e32 v28, v96, v33
	v_mul_f32_e32 v29, v97, v52
	v_mul_f32_e32 v30, v98, v53
	v_mul_f32_e32 v31, v99, v54
	v_cvt_pk_bf16_f32 v28, v28, v29
	v_cvt_pk_bf16_f32 v29, v30, v31
	global_store_dwordx2 v[34:35], v[28:29], off
	v_mul_f32_e32 v33, v32, v58
	v_mul_f32_e32 v52, v32, v59
	v_mul_f32_e32 v53, v32, v60
	v_mul_f32_e32 v54, v32, v61
	v_cmp_lt_i32_e32 vcc, s5, v27
	s_or_b64 s[10:11], vcc, s[10:11]
	v_mul_f32_e32 v28, v100, v33
	v_mul_f32_e32 v29, v101, v52
	v_mul_f32_e32 v30, v102, v53
	v_mul_f32_e32 v31, v103, v54
	v_cvt_pk_bf16_f32 v28, v28, v29
	v_cvt_pk_bf16_f32 v29, v30, v31
	global_store_dwordx2 v[34:35], v[28:29], off offset:512
	v_mul_f32_e32 v33, v32, v62
	v_mul_f32_e32 v52, v32, v63
	v_mul_f32_e32 v53, v32, v64
	v_mul_f32_e32 v54, v32, v65
	v_mul_f32_e32 v28, v104, v33
	v_mul_f32_e32 v29, v105, v52
	v_mul_f32_e32 v30, v106, v53
	v_mul_f32_e32 v31, v107, v54
	v_cvt_pk_bf16_f32 v28, v28, v29
	v_cvt_pk_bf16_f32 v29, v30, v31
	global_store_dwordx2 v[34:35], v[28:29], off offset:1024
	v_mul_f32_e32 v33, v32, v66
	v_mul_f32_e32 v52, v32, v67
	v_mul_f32_e32 v53, v32, v68
	v_mul_f32_e32 v54, v32, v69
	v_mul_f32_e32 v28, v108, v33
	v_mul_f32_e32 v29, v109, v52
	v_mul_f32_e32 v30, v110, v53
	v_mul_f32_e32 v31, v111, v54
	v_cvt_pk_bf16_f32 v28, v28, v29
	v_cvt_pk_bf16_f32 v29, v30, v31
	global_store_dwordx2 v[34:35], v[28:29], off offset:1536
	v_mul_f32_e32 v33, v32, v36
	v_mul_f32_e32 v36, v32, v38
	v_mul_f32_e32 v38, v32, v40
	v_mul_f32_e32 v40, v32, v42
	v_mul_f32_e32 v28, v33, v112
	v_mul_f32_e32 v29, v36, v113
	v_mul_f32_e32 v30, v38, v114
	v_mul_f32_e32 v31, v40, v115
	v_cvt_pk_bf16_f32 v28, v28, v29
	v_cvt_pk_bf16_f32 v29, v30, v31
	global_store_dwordx2 v[34:35], v[28:29], off offset:2048
	v_mul_f32_e32 v33, v32, v37
	v_mul_f32_e32 v36, v32, v39
	v_mul_f32_e32 v37, v32, v41
	v_mul_f32_e32 v38, v32, v43
	v_mul_f32_e32 v28, v33, v116
	v_mul_f32_e32 v29, v36, v117
	v_mul_f32_e32 v30, v37, v118
	v_mul_f32_e32 v31, v38, v119
	v_cvt_pk_bf16_f32 v28, v28, v29
	v_cvt_pk_bf16_f32 v29, v30, v31
	global_store_dwordx2 v[34:35], v[28:29], off offset:2560
	v_mul_f32_e32 v33, v32, v44
	v_mul_f32_e32 v36, v32, v46
	v_mul_f32_e32 v37, v32, v50
	v_mul_f32_e32 v38, v32, v48
	v_mul_f32_e32 v28, v33, v120
	v_mul_f32_e32 v29, v36, v121
	v_mul_f32_e32 v30, v37, v122
	v_mul_f32_e32 v31, v38, v123
	v_cvt_pk_bf16_f32 v28, v28, v29
	v_cvt_pk_bf16_f32 v29, v30, v31
	global_store_dwordx2 v[34:35], v[28:29], off offset:3072
	v_mul_f32_e32 v33, v32, v45
	v_mul_f32_e32 v36, v32, v47
	v_mul_f32_e32 v37, v32, v51
	v_mul_f32_e32 v32, v32, v49
	v_mul_f32_e32 v28, v33, v124
	v_mul_f32_e32 v29, v36, v125
	v_mul_f32_e32 v30, v37, v126
	v_mul_f32_e32 v31, v32, v127
	v_cvt_pk_bf16_f32 v28, v28, v29
	v_cvt_pk_bf16_f32 v29, v30, v31
	global_store_dwordx2 v[34:35], v[28:29], off offset:3584
	s_andn2_b64 exec, exec, s[10:11]
	s_cbranch_execnz .LBB0_309

; template <int DQK, bool ROPEQ, bool ALIBI> ...
;     ...
;     if (ntw > 0) {
;         const float rl = __builtin_amdgcn_rcpf(l_reg);
; #pragma unroll
;         for (int d = 0; d < 4; ++d)
; #pragma unroll
;             for (int r = 0; r < 16; ++r) o[d][r] *= rl;
;     }
; __global__ void __launch_bounds__(512, 2) mega(Args a) {
;     ...
;                 if (ntw > 0) {
;                     float ssq = 0.f;
; #pragma unroll
;                     for (int d = 0; d < 4; ++d) {
; #pragma unroll
;                         for (int r = 0; r < 16; r += 4) { const f32x4 s1 = *(const f32x4*)(sp + d * 16 + r);
; #pragma unroll
;                             for (int k = 0; k < 4; ++k) { const float x = s1[k] - lam * o[d][r + k]; o[d][r + k] = x; ssq += x * x; } }
;                         asm volatile("" ::: "memory"); }
.LBB0_1219:
	s_and_b64 vcc, exec, s[20:21]
	s_cbranch_vccz .LBB0_1168
	v_rcp_f32_e32 v66, v139
	s_mov_b32 s0, 0x800000
	v_mul_f32_e32 v68, v66, v50
	v_mul_f32_e32 v78, v66, v60
	v_mul_f32_e32 v80, v66, v64
	v_mul_f32_e32 v86, v66, v34
	v_mul_f32_e32 v89, v66, v38
	v_mul_f32_e32 v92, v66, v42
	v_mul_f32_e32 v93, v66, v43
	v_mul_f32_e32 v94, v66, v44
	v_mul_f32_e32 v95, v66, v45
	v_mul_f32_e32 v71, v66, v18
	v_mul_f32_e32 v69, v66, v19
	v_mul_f32_e32 v67, v66, v20
	v_mul_f32_e32 v64, v66, v21
	v_mul_f32_e32 v60, v66, v23
	v_mul_f32_e32 v50, v66, v26
	v_mul_f32_e32 v38, v66, v29
	v_mul_f32_e32 v34, v66, v30
	v_mul_f32_e32 v76, v66, v31
	v_mul_f32_e32 v29, v66, v32
	v_mul_f32_e32 v26, v66, v33
	v_mul_f32_e32 v75, v66, v2
	v_mul_f32_e32 v74, v66, v3
	v_mul_f32_e32 v73, v66, v4
	v_mul_f32_e32 v23, v66, v5
	global_load_dwordx4 v[2:5], v[134:135], off offset:48
	global_load_dwordx4 v[18:21], v[134:135], off offset:32
	global_load_dwordx4 v[30:33], v[134:135], off offset:16
	global_load_dwordx4 v[42:45], v[134:135], off
	v_mul_f32_e32 v51, v66, v51
	v_mul_f32_e32 v55, v66, v55
	v_mul_f32_e32 v77, v66, v58
	v_mul_f32_e32 v59, v66, v59
	v_mul_f32_e32 v61, v66, v61
	v_mul_f32_e32 v79, v66, v62
	v_mul_f32_e32 v63, v66, v63
	v_mul_f32_e32 v65, v66, v65
	v_mul_f32_e32 v72, v66, v56
	v_mul_f32_e32 v87, v66, v36
	v_mul_f32_e32 v88, v66, v37
	v_mul_f32_e32 v90, v66, v40
	v_mul_f32_e32 v91, v66, v41
	v_mul_f32_e32 v98, v66, v48
	v_mul_f32_e32 v58, v66, v24
	v_mul_f32_e32 v56, v66, v25
	v_mul_f32_e32 v41, v66, v28
	v_mul_f32_e32 v52, v66, v52
	v_mul_f32_e32 v53, v66, v53
	v_mul_f32_e32 v70, v66, v54
	v_mul_f32_e32 v57, v66, v57
	v_mul_f32_e32 v35, v66, v35
	v_mul_f32_e32 v39, v66, v39
	v_mul_f32_e32 v96, v66, v46
	v_mul_f32_e32 v97, v66, v47
	v_mul_f32_e32 v99, v66, v49
	v_mul_f32_e32 v46, v66, v27
	v_mul_f32_e32 v62, v66, v22
	v_mul_f32_e32 v22, v66, v6
	v_mul_f32_e32 v6, v66, v7
	s_waitcnt vmcnt(3)
	v_fma_f32 v28, -v130, v63, v3
	s_waitcnt vmcnt(2)
	v_fma_f32 v40, -v130, v59, v19
	s_waitcnt vmcnt(1)
	v_fma_f32 v48, -v130, v55, v31
	s_waitcnt vmcnt(0)
	v_fma_f32 v51, -v130, v51, v43
	v_fma_f32 v43, -v130, v77, v18
	v_fma_f32 v37, -v130, v78, v20
	v_fma_f32 v36, -v130, v61, v21
	v_fma_f32 v31, -v130, v79, v2
	v_fma_f32 v25, -v130, v80, v4
	v_fma_f32 v24, -v130, v65, v5
	global_load_dwordx4 v[2:5], v[134:135], off offset:112
	global_load_dwordx4 v[18:21], v[134:135], off offset:96
	global_load_dwordx4 v[78:81], v[134:135], off offset:80
	global_load_dwordx4 v[82:85], v[134:135], off offset:64
	v_fma_f32 v54, -v130, v68, v42
	v_fma_f32 v52, -v130, v52, v44
	v_fma_f32 v53, -v130, v53, v45
	v_fma_f32 v47, -v130, v70, v30
	v_fma_f32 v44, -v130, v72, v32
	v_fma_f32 v45, -v130, v57, v33
	v_mul_f32_e32 v7, v51, v51
	v_fmac_f32_e32 v7, v54, v54
	v_fmac_f32_e32 v7, v52, v52
	v_fmac_f32_e32 v7, v53, v53
	v_fmac_f32_e32 v7, v47, v47
	v_fmac_f32_e32 v7, v48, v48
	v_fmac_f32_e32 v7, v44, v44
	v_fmac_f32_e32 v7, v45, v45
	v_fmac_f32_e32 v7, v43, v43
	v_fmac_f32_e32 v7, v40, v40
	v_fmac_f32_e32 v7, v37, v37
	v_fmac_f32_e32 v7, v36, v36
	v_fmac_f32_e32 v7, v31, v31
	v_fmac_f32_e32 v7, v28, v28
	v_fmac_f32_e32 v7, v25, v25
	v_fmac_f32_e32 v7, v24, v24
	s_waitcnt vmcnt(3)
	v_fma_f32 v33, -v130, v97, v3
	s_waitcnt vmcnt(2)
	v_fma_f32 v55, -v130, v92, v18
	s_waitcnt vmcnt(1)
	v_fma_f32 v63, -v130, v89, v78
	s_waitcnt vmcnt(0)
	v_fma_f32 v72, -v130, v86, v82
	v_fma_f32 v70, -v130, v35, v83
	v_fma_f32 v68, -v130, v87, v84
	v_fma_f32 v65, -v130, v88, v85
	v_fma_f32 v61, -v130, v39, v79
	v_fma_f32 v59, -v130, v90, v80
	v_fma_f32 v57, -v130, v91, v81
	v_fma_f32 v49, -v130, v93, v19
	v_fma_f32 v42, -v130, v94, v20
	v_fma_f32 v39, -v130, v95, v21
	v_fma_f32 v35, -v130, v96, v2
	v_fma_f32 v30, -v130, v98, v4
	v_fma_f32 v27, -v130, v99, v5
	global_load_dwordx4 v[2:5], v[134:135], off offset:176
	global_load_dwordx4 v[18:21], v[134:135], off offset:160
	global_load_dwordx4 v[78:81], v[134:135], off offset:144
	global_load_dwordx4 v[82:85], v[134:135], off offset:128
	v_fmac_f32_e32 v7, v72, v72
	v_fmac_f32_e32 v7, v70, v70
	v_fmac_f32_e32 v7, v68, v68
	v_fmac_f32_e32 v7, v65, v65
	v_fmac_f32_e32 v7, v63, v63
	v_fmac_f32_e32 v7, v61, v61
	v_fmac_f32_e32 v7, v59, v59
	v_fmac_f32_e32 v7, v57, v57
	v_fmac_f32_e32 v7, v55, v55
	v_fmac_f32_e32 v7, v49, v49
	v_fmac_f32_e32 v7, v42, v42
	v_fmac_f32_e32 v7, v39, v39
	v_fmac_f32_e32 v7, v35, v35
	v_fmac_f32_e32 v7, v33, v33
	v_fmac_f32_e32 v7, v30, v30
	v_fmac_f32_e32 v7, v27, v27
	s_waitcnt vmcnt(3)
	v_fma_f32 v34, -v130, v34, v2
	s_waitcnt vmcnt(2)
	v_fma_f32 v50, -v130, v50, v18
	s_waitcnt vmcnt(1)
	v_fma_f32 v58, -v130, v58, v80
	s_waitcnt vmcnt(0)
	v_fma_f32 v71, -v130, v71, v82
	v_fma_f32 v69, -v130, v69, v83
	v_fma_f32 v67, -v130, v67, v84
	v_fma_f32 v64, -v130, v64, v85
	v_fma_f32 v56, -v130, v56, v81
	v_fma_f32 v46, -v130, v46, v19
	v_fma_f32 v41, -v130, v41, v20
	v_fma_f32 v38, -v130, v38, v21
	v_fma_f32 v32, -v130, v76, v3
	v_fma_f32 v29, -v130, v29, v4
	v_fma_f32 v26, -v130, v26, v5
	global_load_dwordx4 v[2:5], v[134:135], off offset:240
	global_load_dwordx4 v[18:21], v[134:135], off offset:224
	global_load_dwordx4 v[80:83], v[134:135], off offset:208
	global_load_dwordx4 v[84:87], v[134:135], off offset:192
	v_fmac_f32_e32 v7, v71, v71
	v_fmac_f32_e32 v7, v69, v69
	v_fmac_f32_e32 v7, v67, v67
	v_fmac_f32_e32 v7, v64, v64
	v_fma_f32 v62, -v130, v62, v78
	v_fmac_f32_e32 v7, v62, v62
	v_fma_f32 v60, -v130, v60, v79
	v_fmac_f32_e32 v7, v60, v60
	v_fmac_f32_e32 v7, v58, v58
	v_fmac_f32_e32 v7, v56, v56
	v_fmac_f32_e32 v7, v50, v50
	v_fmac_f32_e32 v7, v46, v46
	v_fmac_f32_e32 v7, v41, v41
	v_fmac_f32_e32 v7, v38, v38
	v_fmac_f32_e32 v7, v34, v34
	v_fmac_f32_e32 v7, v32, v32
	v_fmac_f32_e32 v7, v29, v29
	v_fmac_f32_e32 v7, v26, v26
	v_pk_mul_f32 v[8:9], v[66:67], v[8:9] op_sel_hi:[0,1]
	s_waitcnt vmcnt(0)
; __device__ __forceinline__ unsigned cvtpk(float lo, float hi) { unsigned r; asm volatile("v_cvt_pk_bf16_f32 %0, %1, %2" : "=v"(r) : "v"(lo), "v"(hi)); return r; }
; __global__ void __launch_bounds__(512, 2) mega(Args a) {
;     ...
;                     float ssq = 0.f;
; #pragma unroll
;                     for (int d = 0; d < 4; ++d) {
; #pragma unroll
;                         for (int r = 0; r < 16; r += 4) { const f32x4 s1 = *(const f32x4*)(sp + d * 16 + r);
; #pragma unroll
;                             for (int k = 0; k < 4; ++k) { const float x = s1[k] - lam * o[d][r + k]; o[d][r + k] = x; ssq += x * x; } }
;                         asm volatile("" ::: "memory"); }
;                     ssq += __shfl_xor(ssq, 32);
;                     const float rs = rsqrtf(ssq * (1.0f / 128.0f) + EPS) * 0.8f;
;                     bf16_t* orow = xn + (size_t)qrow * DM + h * 128 + 4 * hi;
; #pragma unroll
;                     for (int d = 0; d < 4; ++d)
; #pragma unroll
;                         for (int r4 = 0; r4 < 4; ++r4) { const f32x4 gg = *(const f32x4*)(a.in[16] + d * 32 + r4 * 8 + 4 * hi);
;                             u32x2 w; w.x = cvtpk(o[d][4 * r4] * rs * gg[0], o[d][4 * r4 + 1] * rs * gg[1]); w.y = cvtpk(o[d][4 * r4 + 2] * rs * gg[2], o[d][4 * r4 + 3] * rs * gg[3]);
;                             *(u32x2*)(orow + d * 32 + r4 * 8) = w; }
	v_fma_f32 v78, -v130, v75, v84
	v_fmac_f32_e32 v7, v78, v78
	v_fma_f32 v77, -v130, v74, v85
	v_fmac_f32_e32 v7, v77, v77
	v_fma_f32 v76, -v130, v73, v86
	v_fmac_f32_e32 v7, v76, v76
	v_fma_f32 v75, -v130, v23, v87
	v_fmac_f32_e32 v7, v75, v75
	v_fma_f32 v74, -v130, v22, v80
	v_fmac_f32_e32 v7, v74, v74
	v_fma_f32 v73, -v130, v6, v81
	v_pk_fma_f32 v[22:23], v[130:131], v[8:9], v[82:83] neg_lo:[1,0,0] neg_hi:[1,0,0]
	v_fmac_f32_e32 v7, v73, v73
	v_pk_mul_f32 v[8:9], v[22:23], v[22:23]
	s_nop 0
	v_add_f32_e32 v6, v7, v8
	v_add_f32_e32 v8, v6, v9
	v_pk_mul_f32 v[6:7], v[66:67], v[10:11] op_sel_hi:[0,1]
	v_pk_fma_f32 v[18:19], v[130:131], v[6:7], v[18:19] neg_lo:[1,0,0] neg_hi:[1,0,0]
	s_nop 0
	v_pk_mul_f32 v[6:7], v[18:19], v[18:19]
	s_nop 0
	v_add_f32_e32 v6, v8, v6
	v_add_f32_e32 v8, v6, v7
	v_pk_mul_f32 v[6:7], v[66:67], v[12:13] op_sel_hi:[0,1]
	v_pk_fma_f32 v[10:11], v[130:131], v[6:7], v[20:21] neg_lo:[1,0,0] neg_hi:[1,0,0]
	s_nop 0
	v_pk_mul_f32 v[6:7], v[10:11], v[10:11]
	s_nop 0
	v_add_f32_e32 v6, v8, v6
	v_add_f32_e32 v12, v6, v7
	v_pk_mul_f32 v[6:7], v[66:67], v[14:15] op_sel_hi:[0,1]
	v_pk_fma_f32 v[8:9], v[130:131], v[6:7], v[2:3] neg_lo:[1,0,0] neg_hi:[1,0,0]
	s_nop 0
	v_pk_mul_f32 v[2:3], v[8:9], v[8:9]
	s_nop 0
	v_add_f32_e32 v2, v12, v2
	v_add_f32_e32 v12, v2, v3
	v_pk_mul_f32 v[2:3], v[66:67], v[16:17] op_sel_hi:[0,1]
	v_pk_fma_f32 v[6:7], v[130:131], v[2:3], v[4:5] neg_lo:[1,0,0] neg_hi:[1,0,0]
	v_and_b32_e32 v4, 64, v231
	v_pk_mul_f32 v[2:3], v[6:7], v[6:7]
	v_add_u32_e32 v4, 64, v4
	v_add_f32_e32 v2, v12, v2
	v_add_f32_e32 v2, v2, v3
	v_xor_b32_e32 v3, 32, v231
	v_cmp_lt_i32_e32 vcc, v3, v4
	v_lshlrev_b32_e32 v4, 1, v154
	v_mov_b32_e32 v5, v153
	v_cndmask_b32_e32 v3, v231, v3, vcc
	v_lshlrev_b32_e32 v3, 2, v3
	ds_bpermute_b32 v3, v3, v2
	s_waitcnt lgkmcnt(0)
	v_add_f32_e32 v2, v2, v3
	v_fmamk_f32 v2, v2, 0x3c000000, v229
	v_cmp_gt_f32_e32 vcc, s0, v2
	v_mul_f32_e32 v3, 0x4b800000, v2
	v_readlane_b32 s0, v244, 38
	v_cndmask_b32_e32 v2, v2, v3, vcc
	v_rsq_f32_e32 v2, v2
	s_lshl_b32 s4, s0, 1
	v_mul_f32_e32 v3, 0x45800000, v2
	v_cndmask_b32_e32 v2, v2, v3, vcc
	v_mul_f32_e32 v14, 0x3f4ccccd, v2
	v_lshlrev_b64 v[2:3], 12, v[144:145]
	v_lshl_add_u64 v[2:3], s[84:85], 0, v[2:3]
	v_lshl_add_u64 v[2:3], v[2:3], 0, s[4:5]
	v_lshl_add_u64 v[12:13], v[2:3], 0, v[4:5]
	global_load_dwordx4 v[80:83], v[142:143], off
	global_load_dwordx4 v[84:87], v[142:143], off offset:32
	global_load_dwordx4 v[88:91], v[142:143], off offset:64
	global_load_dwordx4 v[92:95], v[142:143], off offset:96
	global_load_dwordx4 v[96:99], v[142:143], off offset:128
	global_load_dwordx4 v[100:103], v[142:143], off offset:160
	global_load_dwordx4 v[104:107], v[142:143], off offset:192
	global_load_dwordx4 v[108:111], v[142:143], off offset:224
	v_mul_f32_e32 v15, v14, v54
	v_mul_f32_e32 v8, v14, v8
	s_waitcnt vmcnt(0)
; __device__ __forceinline__ unsigned cvtpk(float lo, float hi) { unsigned r; asm volatile("v_cvt_pk_bf16_f32 %0, %1, %2" : "=v"(r) : "v"(lo), "v"(hi)); return r; }
; __global__ void __launch_bounds__(512, 2) mega(Args a) {
;     ...
; #pragma unroll
;                     for (int d = 0; d < 4; ++d)
; #pragma unroll
;                         for (int r4 = 0; r4 < 4; ++r4) { const f32x4 gg = *(const f32x4*)(a.in[16] + d * 32 + r4 * 8 + 4 * hi);
;                             u32x2 w; w.x = cvtpk(o[d][4 * r4] * rs * gg[0], o[d][4 * r4 + 1] * rs * gg[1]); w.y = cvtpk(o[d][4 * r4 + 2] * rs * gg[2], o[d][4 * r4 + 3] * rs * gg[3]);
;                             *(u32x2*)(orow + d * 32 + r4 * 8) = w; }
	v_mul_f32_e32 v2, v80, v15
	v_mul_f32_e32 v15, v14, v51
	v_mul_f32_e32 v3, v81, v15
	v_cvt_pk_bf16_f32 v2, v2, v3
	v_mul_f32_e32 v3, v14, v52
	v_mul_f32_e32 v3, v82, v3
	v_mul_f32_e32 v4, v14, v53
	v_mul_f32_e32 v4, v83, v4
	v_cvt_pk_bf16_f32 v3, v3, v4
	global_store_dwordx2 v[12:13], v[2:3], off
	v_mul_f32_e32 v15, v14, v47
	v_mul_f32_e32 v2, v84, v15
	v_mul_f32_e32 v15, v14, v48
	v_mul_f32_e32 v3, v85, v15
	v_cvt_pk_bf16_f32 v2, v2, v3
	v_mul_f32_e32 v3, v14, v44
	v_mul_f32_e32 v3, v86, v3
	v_mul_f32_e32 v4, v14, v45
	v_mul_f32_e32 v4, v87, v4
	v_cvt_pk_bf16_f32 v3, v3, v4
	global_store_dwordx2 v[12:13], v[2:3], off offset:16
	v_mul_f32_e32 v15, v14, v43
	v_mul_f32_e32 v2, v88, v15
	v_mul_f32_e32 v15, v14, v40
	v_mul_f32_e32 v3, v89, v15
	v_cvt_pk_bf16_f32 v2, v2, v3
	v_mul_f32_e32 v3, v14, v37
	v_mul_f32_e32 v3, v90, v3
	v_mul_f32_e32 v4, v14, v36
	v_mul_f32_e32 v4, v91, v4
	v_cvt_pk_bf16_f32 v3, v3, v4
	global_store_dwordx2 v[12:13], v[2:3], off offset:32
	v_mul_f32_e32 v15, v14, v31
	v_mul_f32_e32 v2, v92, v15
	v_mul_f32_e32 v15, v14, v28
	v_mul_f32_e32 v3, v93, v15
	v_cvt_pk_bf16_f32 v2, v2, v3
	v_mul_f32_e32 v3, v14, v25
	v_mul_f32_e32 v3, v94, v3
	v_mul_f32_e32 v4, v14, v24
	v_mul_f32_e32 v4, v95, v4
	v_cvt_pk_bf16_f32 v3, v3, v4
	global_store_dwordx2 v[12:13], v[2:3], off offset:48
	v_mul_f32_e32 v15, v14, v72
	v_mul_f32_e32 v2, v96, v15
	v_mul_f32_e32 v15, v14, v70
	v_mul_f32_e32 v3, v97, v15
	v_cvt_pk_bf16_f32 v2, v2, v3
	v_mul_f32_e32 v3, v14, v68
	v_mul_f32_e32 v3, v98, v3
	v_mul_f32_e32 v4, v14, v65
	v_mul_f32_e32 v4, v99, v4
	v_cvt_pk_bf16_f32 v3, v3, v4
	global_store_dwordx2 v[12:13], v[2:3], off offset:64
	v_mul_f32_e32 v15, v14, v63
	v_mul_f32_e32 v2, v100, v15
	v_mul_f32_e32 v15, v14, v61
	v_mul_f32_e32 v3, v101, v15
	v_cvt_pk_bf16_f32 v2, v2, v3
	v_mul_f32_e32 v3, v14, v59
	v_mul_f32_e32 v3, v102, v3
	v_mul_f32_e32 v4, v14, v57
	v_mul_f32_e32 v4, v103, v4
	v_cvt_pk_bf16_f32 v3, v3, v4
	global_store_dwordx2 v[12:13], v[2:3], off offset:80
	v_mul_f32_e32 v15, v14, v55
	v_mul_f32_e32 v2, v104, v15
	v_mul_f32_e32 v15, v14, v49
	v_mul_f32_e32 v3, v105, v15
	v_cvt_pk_bf16_f32 v2, v2, v3
	v_mul_f32_e32 v3, v14, v42
	v_mul_f32_e32 v3, v106, v3
	v_mul_f32_e32 v4, v14, v39
	v_mul_f32_e32 v4, v107, v4
	v_cvt_pk_bf16_f32 v3, v3, v4
	global_store_dwordx2 v[12:13], v[2:3], off offset:96
	v_mul_f32_e32 v15, v14, v35
	v_mul_f32_e32 v2, v108, v15
	v_mul_f32_e32 v15, v14, v33
	v_mul_f32_e32 v3, v109, v15
	v_cvt_pk_bf16_f32 v2, v2, v3
	v_mul_f32_e32 v3, v14, v30
	v_mul_f32_e32 v3, v110, v3
	v_mul_f32_e32 v4, v14, v27
	v_mul_f32_e32 v4, v111, v4
	v_cvt_pk_bf16_f32 v3, v3, v4
	global_store_dwordx2 v[12:13], v[2:3], off offset:112
	global_load_dwordx4 v[80:83], v[142:143], off offset:256
	global_load_dwordx4 v[84:87], v[142:143], off offset:288
	global_load_dwordx4 v[88:91], v[142:143], off offset:320
	global_load_dwordx4 v[92:95], v[142:143], off offset:352
	global_load_dwordx4 v[96:99], v[142:143], off offset:384
	global_load_dwordx4 v[100:103], v[142:143], off offset:416
	global_load_dwordx4 v[104:107], v[142:143], off offset:448
	global_load_dwordx4 v[108:111], v[142:143], off offset:480
	v_mul_f32_e32 v15, v14, v71
	s_waitcnt vmcnt(0)
	v_mul_f32_e32 v2, v80, v15
	v_mul_f32_e32 v15, v14, v69
	v_mul_f32_e32 v3, v81, v15
	v_cvt_pk_bf16_f32 v2, v2, v3
	v_mul_f32_e32 v3, v14, v67
	v_mul_f32_e32 v3, v82, v3
	v_mul_f32_e32 v4, v14, v64
	v_mul_f32_e32 v4, v83, v4
	v_cvt_pk_bf16_f32 v3, v3, v4
	global_store_dwordx2 v[12:13], v[2:3], off offset:128
	v_mul_f32_e32 v15, v14, v62
	v_mul_f32_e32 v2, v84, v15
	v_mul_f32_e32 v15, v14, v60
	v_mul_f32_e32 v3, v85, v15
	v_cvt_pk_bf16_f32 v2, v2, v3
	v_mul_f32_e32 v3, v14, v58
	v_mul_f32_e32 v3, v86, v3
	v_mul_f32_e32 v4, v14, v56
	v_mul_f32_e32 v4, v87, v4
	v_cvt_pk_bf16_f32 v3, v3, v4
	global_store_dwordx2 v[12:13], v[2:3], off offset:144
	v_mul_f32_e32 v15, v14, v50
	v_mul_f32_e32 v2, v88, v15
	v_mul_f32_e32 v15, v14, v46
	v_mul_f32_e32 v3, v89, v15
	v_cvt_pk_bf16_f32 v2, v2, v3
	v_mul_f32_e32 v3, v14, v41
	v_mul_f32_e32 v3, v90, v3
	v_mul_f32_e32 v4, v14, v38
	v_mul_f32_e32 v4, v91, v4
	v_cvt_pk_bf16_f32 v3, v3, v4
	global_store_dwordx2 v[12:13], v[2:3], off offset:160
	v_mul_f32_e32 v15, v14, v34
	v_mul_f32_e32 v2, v92, v15
	v_mul_f32_e32 v15, v14, v32
	v_mul_f32_e32 v3, v93, v15
	v_cvt_pk_bf16_f32 v2, v2, v3
	v_mul_f32_e32 v3, v14, v29
	v_mul_f32_e32 v3, v94, v3
	v_mul_f32_e32 v4, v14, v26
	v_mul_f32_e32 v4, v95, v4
	v_cvt_pk_bf16_f32 v3, v3, v4
	global_store_dwordx2 v[12:13], v[2:3], off offset:176
	v_mul_f32_e32 v15, v14, v78
	v_mul_f32_e32 v2, v96, v15
	v_mul_f32_e32 v15, v14, v77
	v_mul_f32_e32 v3, v97, v15
	v_cvt_pk_bf16_f32 v2, v2, v3
	v_mul_f32_e32 v3, v14, v76
	v_mul_f32_e32 v3, v98, v3
	v_mul_f32_e32 v4, v14, v75
	v_mul_f32_e32 v4, v99, v4
	v_cvt_pk_bf16_f32 v3, v3, v4
	global_store_dwordx2 v[12:13], v[2:3], off offset:192
	v_mul_f32_e32 v15, v14, v74
	v_mul_f32_e32 v2, v100, v15
	v_mul_f32_e32 v15, v14, v73
	v_mul_f32_e32 v3, v101, v15
	v_cvt_pk_bf16_f32 v2, v2, v3
	v_mul_f32_e32 v3, v14, v22
	v_mul_f32_e32 v3, v102, v3
	v_mul_f32_e32 v4, v14, v23
	v_mul_f32_e32 v4, v103, v4
	v_cvt_pk_bf16_f32 v3, v3, v4
	global_store_dwordx2 v[12:13], v[2:3], off offset:208
	v_mul_f32_e32 v15, v14, v18
	v_mul_f32_e32 v2, v104, v15
	v_mul_f32_e32 v15, v14, v19
	v_mul_f32_e32 v3, v105, v15
	v_cvt_pk_bf16_f32 v2, v2, v3
	v_mul_f32_e32 v3, v14, v10
	v_mul_f32_e32 v3, v106, v3
	v_mul_f32_e32 v4, v14, v11
	v_mul_f32_e32 v4, v107, v4
	v_cvt_pk_bf16_f32 v3, v3, v4
	global_store_dwordx2 v[12:13], v[2:3], off offset:224
	v_mul_f32_e32 v2, v108, v8
	v_mul_f32_e32 v8, v14, v9
	v_mul_f32_e32 v3, v109, v8
	v_cvt_pk_bf16_f32 v2, v2, v3
	v_mul_f32_e32 v3, v14, v6
	v_mul_f32_e32 v3, v110, v3
	v_mul_f32_e32 v4, v14, v7
	v_mul_f32_e32 v4, v111, v4
	v_cvt_pk_bf16_f32 v3, v3, v4
	global_store_dwordx2 v[12:13], v[2:3], off offset:240
	s_branch .LBB0_1168

; __device__ __forceinline__ void norm_rows_mixed(const bf16_t* xb, const float* xs, const float* g, bf16_t* xn) {
;     const int lane = threadIdx.x & 63, gw = blockIdx.x * 8 + (threadIdx.x >> 6), nw = gridDim.x * 8;
;     for (int row = gw; row < MP; row += nw) {
;         u32x2 w[8]; float ss = 0.f;
; #pragma unroll
;         for (int i = 0; i < 8; ++i) w[i] = *(const u32x2*)(xb + (size_t)row * DM + (i * 64 + lane) * 4);
; #pragma unroll
;         for (int i = 0; i < 8; ++i) { const float a0 = __uint_as_float(w[i].x << 16), a1 = __uint_as_float(w[i].x & 0xffff0000u), a2 = __uint_as_float(w[i].y << 16), a3 = __uint_as_float(w[i].y & 0xffff0000u);
;             ss += a0 * a0 + a1 * a1 + a2 * a2 + a3 * a3; }
;         ss = wave_sum(ss); const float rs = rsqrtf(ss * (1.0f / DM) + EPS);
; #pragma unroll
;         for (int i = 0; i < 8; ++i) { const f32x4 gg = *(const f32x4*)(g + (i * 64 + lane) * 4);
; __global__ void __launch_bounds__(512, 2) mega(Args a) {
;     ...
;     if (IN(9)) for (int rep_ = 0; rep_ < REPS(9); ++rep_) { if (rep_) grid.sync(); norm_rows_mixed(XS, ys, a.in[22], xn); }
.LBB0_1421:
	s_cmp_lt_i32 s78, 10
	s_cselect_b64 s[0:1], -1, 0
	s_and_b64 s[4:5], s[0:1], s[4:5]
	s_andn2_b64 vcc, exec, s[4:5]
	s_cbranch_vccnz .LBB0_1429
	v_readlane_b32 s8, v244, 8
	v_mov_b32_e32 v151, 0
	v_readlane_b32 s12, v244, 12
	v_readlane_b32 s13, v244, 13
	v_readlane_b32 s20, v244, 20
	v_readlane_b32 s21, v244, 21
	s_mov_b64 s[12:13], s[20:21]
	v_or_b32_e32 v4, 0x1000, v150
	s_waitcnt lgkmcnt(0)
	v_mov_b32_e32 v5, v151
	v_lshl_add_u64 v[8:9], s[12:13], 0, v[4:5]
	v_or_b32_e32 v4, 0x1400, v150
	v_lshl_add_u32 v2, s86, 3, v213
	s_mov_b32 s1, 0x8000
	v_lshl_add_u64 v[6:7], s[12:13], 0, v[150:151]
	v_lshl_add_u64 v[10:11], s[12:13], 0, v[4:5]
	v_or_b32_e32 v4, 0x1800, v150
	v_or_b32_e32 v150, 0x1c00, v150
	s_lshl_b32 s0, s88, 3
	v_cmp_gt_i32_e32 vcc, s1, v2
	v_lshl_add_u64 v[12:13], s[12:13], 0, v[4:5]
	v_lshl_add_u64 v[14:15], s[12:13], 0, v[150:151]
	v_ashrrev_i32_e32 v3, 31, v2
	v_readlane_b32 s9, v244, 9
	v_readlane_b32 s10, v244, 10
	v_readlane_b32 s11, v244, 11
	v_readlane_b32 s14, v244, 14
	v_readlane_b32 s15, v244, 15
	v_readlane_b32 s16, v244, 16
	v_readlane_b32 s17, v244, 17
	v_readlane_b32 s18, v244, 18
	v_readlane_b32 s19, v244, 19
	v_readlane_b32 s22, v244, 22
	v_readlane_b32 s23, v244, 23
	s_and_saveexec_b64 s[6:7], vcc
	s_cbranch_execz .LBB0_1425
	v_mbcnt_hi_u32_b32 v4, -1, v147
	v_and_b32_e32 v5, 64, v4
	v_add_u32_e32 v5, 64, v5
	v_xor_b32_e32 v16, 32, v4
	v_cmp_lt_i32_e32 vcc, v16, v5
	s_ashr_i32 s1, s0, 31
	v_lshlrev_b32_e32 v150, 3, v148
	v_cndmask_b32_e32 v16, v4, v16, vcc
	v_lshlrev_b32_e32 v18, 2, v16
	v_xor_b32_e32 v16, 16, v4
	v_cmp_lt_i32_e32 vcc, v16, v5
	s_lshl_b64 s[8:9], s[0:1], 12
	s_mov_b64 s[10:11], 0
	v_cndmask_b32_e32 v16, v4, v16, vcc
	v_lshlrev_b32_e32 v19, 2, v16
	v_xor_b32_e32 v16, 8, v4
	v_cmp_lt_i32_e32 vcc, v16, v5
	v_mov_b32_e32 v24, 0x358637bd
	s_mov_b32 s1, 0x800000
	v_cndmask_b32_e32 v16, v4, v16, vcc
	v_lshlrev_b32_e32 v20, 2, v16
	v_xor_b32_e32 v16, 4, v4
	v_cmp_lt_i32_e32 vcc, v16, v5
	s_mov_b32 s2, 0x5d85000
	s_movk_i32 s3, 0x7fff
	v_cndmask_b32_e32 v16, v4, v16, vcc
	v_lshlrev_b32_e32 v21, 2, v16
	v_xor_b32_e32 v16, 2, v4
	v_cmp_lt_i32_e32 vcc, v16, v5
	v_mov_b32_e32 v25, v2
	s_nop 0
	v_cndmask_b32_e32 v16, v4, v16, vcc
	v_lshlrev_b32_e32 v22, 2, v16
	v_xor_b32_e32 v16, 1, v4
	v_cmp_lt_i32_e32 vcc, v16, v5
	s_nop 1
	v_cndmask_b32_e32 v4, v4, v16, vcc
	v_lshlrev_b64 v[16:17], 12, v[2:3]
	v_lshlrev_b32_e32 v23, 2, v4
	v_lshl_add_u64 v[4:5], s[76:77], 0, v[16:17]
	v_lshl_add_u64 v[16:17], s[74:75], 0, v[16:17]
	global_load_dwordx4 v[96:99], v[6:7], off
	global_load_dwordx4 v[100:103], v[6:7], off offset:1024
	global_load_dwordx4 v[104:107], v[6:7], off offset:2048
	global_load_dwordx4 v[108:111], v[6:7], off offset:3072
	global_load_dwordx4 v[112:115], v[8:9], off
	global_load_dwordx4 v[116:119], v[10:11], off
	global_load_dwordx4 v[120:123], v[12:13], off
	global_load_dwordx4 v[124:127], v[14:15], off
; __device__ __forceinline__ unsigned cvtpk(float lo, float hi) { unsigned r; asm volatile("v_cvt_pk_bf16_f32 %0, %1, %2" : "=v"(r) : "v"(lo), "v"(hi)); return r; }
; __device__ __forceinline__ void norm_rows_mixed(const bf16_t* xb, const float* xs, const float* g, bf16_t* xn) {
;     ...
;     for (int row = gw; row < MP; row += nw) {
;         u32x2 w[8]; float ss = 0.f;
; #pragma unroll
;         for (int i = 0; i < 8; ++i) w[i] = *(const u32x2*)(xb + (size_t)row * DM + (i * 64 + lane) * 4);
; #pragma unroll
;         for (int i = 0; i < 8; ++i) { const float a0 = __uint_as_float(w[i].x << 16), a1 = __uint_as_float(w[i].x & 0xffff0000u), a2 = __uint_as_float(w[i].y << 16), a3 = __uint_as_float(w[i].y & 0xffff0000u);
;             ss += a0 * a0 + a1 * a1 + a2 * a2 + a3 * a3; }
;         ss = wave_sum(ss); const float rs = rsqrtf(ss * (1.0f / DM) + EPS);
; #pragma unroll
;         for (int i = 0; i < 8; ++i) { const f32x4 gg = *(const f32x4*)(g + (i * 64 + lane) * 4);
;             const float a0 = __uint_as_float(w[i].x << 16), a1 = __uint_as_float(w[i].x & 0xffff0000u), a2 = __uint_as_float(w[i].y << 16), a3 = __uint_as_float(w[i].y & 0xffff0000u);
;             u32x2 o; o.x = cvtpk(a0 * rs * gg[0], a1 * rs * gg[1]); o.y = cvtpk(a2 * rs * gg[2], a3 * rs * gg[3]);
;             *(u32x2*)(xn + (size_t)row * DM + (i * 64 + lane) * 4) = o; }
.LBB0_1424:
	v_lshl_add_u64 v[30:31], v[16:17], 0, v[150:151]
	global_load_dwordx2 v[34:35], v[30:31], off
	global_load_dwordx2 v[36:37], v[30:31], off offset:512
	global_load_dwordx2 v[38:39], v[30:31], off offset:1024
	global_load_dwordx2 v[40:41], v[30:31], off offset:1536
	global_load_dwordx2 v[42:43], v[30:31], off offset:2560
	global_load_dwordx2 v[44:45], v[30:31], off offset:2048
	global_load_dwordx2 v[46:47], v[30:31], off offset:3584
	global_load_dwordx2 v[48:49], v[30:31], off offset:3072
	v_lshl_add_u64 v[32:33], v[4:5], 0, v[150:151]
	v_add_co_u32_e32 v30, vcc, s2, v32
	v_add_u32_e32 v25, s0, v25
	s_nop 0
	v_addc_co_u32_e32 v31, vcc, 0, v33, vcc
	v_lshl_add_u64 v[4:5], v[4:5], 0, s[8:9]
	v_lshl_add_u64 v[16:17], v[16:17], 0, s[8:9]
	s_waitcnt vmcnt(0)
	v_and_b32_e32 v53, 0xffff0000, v34
	v_and_b32_e32 v57, 0xffff0000, v36
	v_lshlrev_b32_e32 v52, 16, v34
	v_lshlrev_b32_e32 v56, 16, v36
	v_and_b32_e32 v61, 0xffff0000, v38
	v_mul_f32_e32 v68, v53, v53
	v_mul_f32_e32 v69, v57, v57
	v_lshlrev_b32_e32 v54, 16, v35
	v_lshlrev_b32_e32 v58, 16, v37
	v_lshlrev_b32_e32 v60, 16, v38
	v_and_b32_e32 v65, 0xffff0000, v40
	v_mul_f32_e32 v70, v61, v61
	v_fmac_f32_e32 v68, v52, v52
	v_fmac_f32_e32 v69, v56, v56
	v_and_b32_e32 v55, 0xffff0000, v35
	v_and_b32_e32 v59, 0xffff0000, v37
	v_lshlrev_b32_e32 v62, 16, v39
	v_lshlrev_b32_e32 v64, 16, v40
	v_and_b32_e32 v35, 0xffff0000, v42
	v_and_b32_e32 v34, 0xffff0000, v44
	v_mul_f32_e32 v71, v65, v65
	v_fmac_f32_e32 v70, v60, v60
	v_fmac_f32_e32 v68, v54, v54
	v_fmac_f32_e32 v69, v58, v58
	v_and_b32_e32 v63, 0xffff0000, v39
	v_lshlrev_b32_e32 v66, 16, v41
	v_and_b32_e32 v67, 0xffff0000, v41
	v_lshlrev_b32_e32 v33, 16, v42
	v_lshlrev_b32_e32 v32, 16, v44
	v_lshlrev_b32_e32 v37, 16, v43
	v_and_b32_e32 v39, 0xffff0000, v43
	v_lshlrev_b32_e32 v41, 16, v46
	v_lshlrev_b32_e32 v40, 16, v48
	v_and_b32_e32 v43, 0xffff0000, v46
	v_and_b32_e32 v42, 0xffff0000, v48
	v_lshlrev_b32_e32 v44, 16, v49
	v_and_b32_e32 v46, 0xffff0000, v49
	v_pk_mul_f32 v[48:49], v[34:35], v[34:35]
	v_fmac_f32_e32 v71, v64, v64
	v_fmac_f32_e32 v70, v62, v62
	v_fmac_f32_e32 v68, v55, v55
	v_fmac_f32_e32 v69, v59, v59
	v_lshlrev_b32_e32 v36, 16, v45
	v_pk_fma_f32 v[48:49], v[32:33], v[32:33], v[48:49]
	v_fmac_f32_e32 v71, v66, v66
	v_fmac_f32_e32 v70, v63, v63
	v_add_f32_e32 v68, v68, v69
	v_and_b32_e32 v38, 0xffff0000, v45
	v_pk_mul_f32 v[50:51], v[42:43], v[42:43]
	v_pk_fma_f32 v[48:49], v[36:37], v[36:37], v[48:49]
	v_fmac_f32_e32 v71, v67, v67
	v_add_f32_e32 v68, v68, v70
	v_lshlrev_b32_e32 v45, 16, v47
	v_pk_fma_f32 v[50:51], v[40:41], v[40:41], v[50:51]
	v_pk_fma_f32 v[48:49], v[38:39], v[38:39], v[48:49]
	v_add_f32_e32 v68, v68, v71
	v_and_b32_e32 v47, 0xffff0000, v47
	v_pk_fma_f32 v[50:51], v[44:45], v[44:45], v[50:51]
	v_add_f32_e32 v48, v68, v48
	v_pk_fma_f32 v[50:51], v[46:47], v[46:47], v[50:51]
	v_add_f32_e32 v48, v48, v49
	v_add_f32_e32 v48, v48, v50
	v_add_f32_e32 v48, v48, v51
	ds_bpermute_b32 v49, v18, v48
	s_waitcnt lgkmcnt(0)
	v_add_f32_e32 v48, v48, v49
	ds_bpermute_b32 v49, v19, v48
	s_waitcnt lgkmcnt(0)
	v_add_f32_e32 v48, v48, v49
	ds_bpermute_b32 v49, v20, v48
	s_waitcnt lgkmcnt(0)
	v_add_f32_e32 v48, v48, v49
	ds_bpermute_b32 v49, v21, v48
	s_waitcnt lgkmcnt(0)
	v_add_f32_e32 v48, v48, v49
	ds_bpermute_b32 v49, v22, v48
	s_waitcnt lgkmcnt(0)
	v_add_f32_e32 v48, v48, v49
	ds_bpermute_b32 v49, v23, v48
	s_waitcnt lgkmcnt(0)
	v_add_f32_e32 v48, v48, v49
	v_fmamk_f32 v48, v48, 0x3a000000, v24
	v_mul_f32_e32 v49, 0x4b800000, v48
	v_cmp_gt_f32_e32 vcc, s1, v48
	s_nop 1
	v_cndmask_b32_e32 v48, v48, v49, vcc
	v_rsq_f32_e32 v48, v48
	s_nop 0
	v_mul_f32_e32 v49, 0x45800000, v48
	v_cndmask_b32_e32 v48, v48, v49, vcc
	v_mul_f32_e32 v49, v48, v52
	v_mul_f32_e32 v50, v48, v53
	v_mul_f32_e32 v51, v48, v54
	v_mul_f32_e32 v52, v48, v55
	v_mul_f32_e32 v26, v96, v49
	v_mul_f32_e32 v27, v97, v50
	v_mul_f32_e32 v28, v98, v51
	v_mul_f32_e32 v29, v99, v52
	v_cvt_pk_bf16_f32 v26, v26, v27
	v_cvt_pk_bf16_f32 v27, v28, v29
	global_store_dwordx2 v[30:31], v[26:27], off
	v_mul_f32_e32 v49, v48, v56
	v_mul_f32_e32 v50, v48, v57
	v_mul_f32_e32 v51, v48, v58
	v_mul_f32_e32 v52, v48, v59
	v_mul_f32_e32 v32, v48, v32
	v_mul_f32_e32 v34, v48, v34
	v_mul_f32_e32 v36, v48, v36
	v_mul_f32_e32 v38, v48, v38
	v_cmp_lt_i32_e32 vcc, s3, v25
	s_or_b64 s[10:11], vcc, s[10:11]
	v_mul_f32_e32 v26, v100, v49
	v_mul_f32_e32 v27, v101, v50
	v_mul_f32_e32 v28, v102, v51
	v_mul_f32_e32 v29, v103, v52
	v_cvt_pk_bf16_f32 v26, v26, v27
	v_cvt_pk_bf16_f32 v27, v28, v29
	global_store_dwordx2 v[30:31], v[26:27], off offset:512
	v_mul_f32_e32 v49, v48, v60
	v_mul_f32_e32 v50, v48, v61
	v_mul_f32_e32 v51, v48, v62
	v_mul_f32_e32 v52, v48, v63
	v_mul_f32_e32 v26, v104, v49
	v_mul_f32_e32 v27, v105, v50
	v_mul_f32_e32 v28, v106, v51
	v_mul_f32_e32 v29, v107, v52
	v_cvt_pk_bf16_f32 v26, v26, v27
	v_cvt_pk_bf16_f32 v27, v28, v29
	global_store_dwordx2 v[30:31], v[26:27], off offset:1024
	v_mul_f32_e32 v49, v48, v64
	v_mul_f32_e32 v50, v48, v65
	v_mul_f32_e32 v51, v48, v66
	v_mul_f32_e32 v52, v48, v67
	v_mul_f32_e32 v26, v108, v49
	v_mul_f32_e32 v27, v109, v50
	v_mul_f32_e32 v28, v110, v51
	v_mul_f32_e32 v29, v111, v52
	v_cvt_pk_bf16_f32 v26, v26, v27
	v_cvt_pk_bf16_f32 v27, v28, v29
	global_store_dwordx2 v[30:31], v[26:27], off offset:1536
	v_mul_f32_e32 v26, v32, v112
	v_mul_f32_e32 v27, v34, v113
	v_mul_f32_e32 v28, v36, v114
	v_mul_f32_e32 v29, v38, v115
	v_cvt_pk_bf16_f32 v26, v26, v27
	v_cvt_pk_bf16_f32 v27, v28, v29
	global_store_dwordx2 v[30:31], v[26:27], off offset:2048
	v_mul_f32_e32 v32, v48, v33
	v_mul_f32_e32 v33, v48, v35
	v_mul_f32_e32 v34, v48, v37
	v_mul_f32_e32 v35, v48, v39
	v_mul_f32_e32 v26, v32, v116
	v_mul_f32_e32 v27, v33, v117
	v_mul_f32_e32 v28, v34, v118
	v_mul_f32_e32 v29, v35, v119
	v_cvt_pk_bf16_f32 v26, v26, v27
	v_cvt_pk_bf16_f32 v27, v28, v29
	global_store_dwordx2 v[30:31], v[26:27], off offset:2560
	v_mul_f32_e32 v32, v48, v40
	v_mul_f32_e32 v33, v48, v42
	v_mul_f32_e32 v34, v48, v44
	v_mul_f32_e32 v35, v48, v46
	v_mul_f32_e32 v26, v32, v120
	v_mul_f32_e32 v27, v33, v121
	v_mul_f32_e32 v28, v34, v122
	v_mul_f32_e32 v29, v35, v123
	v_cvt_pk_bf16_f32 v26, v26, v27
	v_cvt_pk_bf16_f32 v27, v28, v29
	global_store_dwordx2 v[30:31], v[26:27], off offset:3072
	v_mul_f32_e32 v32, v48, v41
	v_mul_f32_e32 v33, v48, v43
	v_mul_f32_e32 v34, v48, v45
	v_mul_f32_e32 v35, v48, v47
	v_mul_f32_e32 v26, v32, v124
	v_mul_f32_e32 v27, v33, v125
	v_mul_f32_e32 v28, v34, v126
	v_mul_f32_e32 v29, v35, v127
	v_cvt_pk_bf16_f32 v26, v26, v27
	v_cvt_pk_bf16_f32 v27, v28, v29
	global_store_dwordx2 v[30:31], v[26:27], off offset:3584
	s_andn2_b64 exec, exec, s[10:11]
	s_cbranch_execnz .LBB0_1424

; __global__ void __launch_bounds__(512, 2) mega(Args a) {
;     ...
;         const int gw = blockIdx.x * 8 + (tid >> 6), nw = G * 8; const float* g = a.in[26];
;         for (int row = gw; row < MP; row += nw) {
;             float* xr = y + (size_t)row * DM; u32x2 w[8]; float ss = 0.f;
; #pragma unroll
;             for (int i = 0; i < 8; ++i) w[i] = *(const u32x2*)(xn + (size_t)row * DM + (i * 64 + lane) * 4);
; #pragma unroll
;             for (int i = 0; i < 8; ++i) { const float a0 = __uint_as_float(w[i].x << 16), a1 = __uint_as_float(w[i].x & 0xffff0000u), a2 = __uint_as_float(w[i].y << 16), a3 = __uint_as_float(w[i].y & 0xffff0000u);
;                 ss += a0 * a0 + a1 * a1 + a2 * a2 + a3 * a3; }
;             ss = wave_sum(ss); const float rs = rsqrtf(ss * (1.0f / DM) + EPS);
; #pragma unroll
;             for (int i = 0; i < 8; ++i) { const f32x4 gg = *(const f32x4*)(g + (i * 64 + lane) * 4);
;                 const float a0 = __uint_as_float(w[i].x << 16), a1 = __uint_as_float(w[i].x & 0xffff0000u), a2 = __uint_as_float(w[i].y << 16), a3 = __uint_as_float(w[i].y & 0xffff0000u);
;                 *(f32x4*)(xr + (i * 64 + lane) * 4) = (f32x4){a0 * rs * gg[0], a1 * rs * gg[1], a2 * rs * gg[2], a3 * rs * gg[3]}; }
.LBB0_1690:
	s_cmp_lt_i32 s78, 13
	s_cselect_b64 s[2:3], -1, 0
	s_and_b64 s[0:1], s[2:3], s[0:1]
	s_andn2_b64 vcc, exec, s[0:1]
	s_cbranch_vccnz .LBB0_1697
	v_lshl_add_u32 v6, s86, 3, v213
	s_mov_b32 s1, 0x8000
	v_lshlrev_b32_e32 v0, 2, v148
	s_lshl_b32 s0, s88, 3
	v_cmp_gt_i32_e32 vcc, s1, v6
	v_lshlrev_b32_e32 v4, 2, v0
	s_and_saveexec_b64 s[2:3], vcc
	s_cbranch_execz .LBB0_1694
	v_mbcnt_hi_u32_b32 v0, -1, v147
	v_and_b32_e32 v1, 64, v0
	v_add_u32_e32 v1, 64, v1
	v_xor_b32_e32 v2, 32, v0
	v_cmp_lt_i32_e32 vcc, v2, v1
	s_waitcnt lgkmcnt(0)
	v_mov_b32_e32 v5, 0
	v_ashrrev_i32_e32 v7, 31, v6
	v_cndmask_b32_e32 v2, v0, v2, vcc
	v_lshlrev_b32_e32 v22, 2, v2
	v_xor_b32_e32 v2, 16, v0
	v_cmp_lt_i32_e32 vcc, v2, v1
	s_mov_b64 s[4:5], 0x5d85000
	s_ashr_i32 s1, s0, 31
	v_cndmask_b32_e32 v2, v0, v2, vcc
	v_lshlrev_b32_e32 v23, 2, v2
	v_xor_b32_e32 v2, 8, v0
	v_cmp_lt_i32_e32 vcc, v2, v1
	s_mov_b64 s[6:7], 0x1c00
	v_lshl_add_u64 v[8:9], s[72:73], 0, v[4:5]
	v_cndmask_b32_e32 v2, v0, v2, vcc
	v_lshlrev_b32_e32 v24, 2, v2
	v_xor_b32_e32 v2, 4, v0
	v_cmp_lt_i32_e32 vcc, v2, v1
	s_mov_b64 s[8:9], 0
	s_movk_i32 s10, 0xf000
	v_cndmask_b32_e32 v2, v0, v2, vcc
	v_lshlrev_b32_e32 v25, 2, v2
	v_xor_b32_e32 v2, 2, v0
	v_cmp_lt_i32_e32 vcc, v2, v1
	s_movk_i32 s11, 0x7fff
	s_nop 0
	v_cndmask_b32_e32 v2, v0, v2, vcc
	v_lshlrev_b32_e32 v26, 2, v2
	v_xor_b32_e32 v2, 1, v0
	v_cmp_lt_i32_e32 vcc, v2, v1
	v_mov_b32_e32 v1, v5
	v_mov_b32_e32 v5, 0x358637bd
	v_cndmask_b32_e32 v0, v0, v2, vcc
	v_lshlrev_b32_e32 v27, 2, v0
	v_or_b32_e32 v0, 0x1000, v4
	v_lshl_add_u64 v[10:11], s[72:73], 0, v[0:1]
	v_or_b32_e32 v0, 0x1400, v4
	v_lshl_add_u64 v[12:13], s[72:73], 0, v[0:1]
	v_or_b32_e32 v0, 0x1800, v4
	v_lshl_add_u64 v[14:15], s[72:73], 0, v[0:1]
	v_or_b32_e32 v0, 0x1c00, v4
	v_lshl_add_u64 v[16:17], s[72:73], 0, v[0:1]
	v_lshlrev_b64 v[0:1], 12, v[6:7]
	v_lshl_or_b32 v0, v148, 3, v0
	v_lshl_add_u64 v[0:1], s[76:77], 0, v[0:1]
	v_lshl_add_u64 v[18:19], v[0:1], 0, s[4:5]
	v_lshlrev_b64 v[0:1], 13, v[6:7]
	v_lshl_or_b32 v0, v148, 4, v0
	v_lshl_add_u64 v[0:1], s[74:75], 0, v[0:1]
	s_lshl_b64 s[4:5], s[0:1], 12
	v_lshl_add_u64 v[20:21], v[0:1], 0, s[6:7]
	s_lshl_b64 s[6:7], s[0:1], 13
	s_mov_b32 s1, 0x800000
	v_mov_b32_e32 v7, v6
	global_load_dwordx4 v[96:99], v[8:9], off
	global_load_dwordx4 v[100:103], v[8:9], off offset:1024
	global_load_dwordx4 v[104:107], v[8:9], off offset:2048
	global_load_dwordx4 v[108:111], v[8:9], off offset:3072
	global_load_dwordx4 v[112:115], v[10:11], off
	global_load_dwordx4 v[116:119], v[12:13], off
	global_load_dwordx4 v[120:123], v[14:15], off
	global_load_dwordx4 v[124:127], v[16:17], off
; __global__ void __launch_bounds__(512, 2) mega(Args a) {
;     ...
;         for (int row = gw; row < MP; row += nw) {
;             float* xr = y + (size_t)row * DM; u32x2 w[8]; float ss = 0.f;
; #pragma unroll
;             for (int i = 0; i < 8; ++i) w[i] = *(const u32x2*)(xn + (size_t)row * DM + (i * 64 + lane) * 4);
; #pragma unroll
;             for (int i = 0; i < 8; ++i) { const float a0 = __uint_as_float(w[i].x << 16), a1 = __uint_as_float(w[i].x & 0xffff0000u), a2 = __uint_as_float(w[i].y << 16), a3 = __uint_as_float(w[i].y & 0xffff0000u);
;                 ss += a0 * a0 + a1 * a1 + a2 * a2 + a3 * a3; }
;             ss = wave_sum(ss); const float rs = rsqrtf(ss * (1.0f / DM) + EPS);
; #pragma unroll
;             for (int i = 0; i < 8; ++i) { const f32x4 gg = *(const f32x4*)(g + (i * 64 + lane) * 4);
;                 const float a0 = __uint_as_float(w[i].x << 16), a1 = __uint_as_float(w[i].x & 0xffff0000u), a2 = __uint_as_float(w[i].y << 16), a3 = __uint_as_float(w[i].y & 0xffff0000u);
;                 *(f32x4*)(xr + (i * 64 + lane) * 4) = (f32x4){a0 * rs * gg[0], a1 * rs * gg[1], a2 * rs * gg[2], a3 * rs * gg[3]}; }
;         }
.LBB0_1693:
	global_load_dwordx2 v[28:29], v[18:19], off
	global_load_dwordx2 v[30:31], v[18:19], off offset:512
	global_load_dwordx2 v[32:33], v[18:19], off offset:1024
	global_load_dwordx2 v[34:35], v[18:19], off offset:1536
	global_load_dwordx2 v[36:37], v[18:19], off offset:2048
	global_load_dwordx2 v[38:39], v[18:19], off offset:2560
	global_load_dwordx2 v[40:41], v[18:19], off offset:3072
	global_load_dwordx2 v[42:43], v[18:19], off offset:3584
	v_add_co_u32_e32 v44, vcc, s10, v20
	v_add_u32_e32 v7, s0, v7
	s_nop 0
	v_addc_co_u32_e32 v45, vcc, -1, v21, vcc
	v_lshl_add_u64 v[18:19], v[18:19], 0, s[4:5]
	s_waitcnt vmcnt(0)
	v_lshlrev_b32_e32 v46, 16, v28
	v_and_b32_e32 v47, 0xffff0000, v28
	v_lshlrev_b32_e32 v48, 16, v30
	v_and_b32_e32 v49, 0xffff0000, v30
	v_lshlrev_b32_e32 v28, 16, v29
	v_and_b32_e32 v29, 0xffff0000, v29
	v_and_b32_e32 v59, 0xffff0000, v40
	v_and_b32_e32 v61, 0xffff0000, v42
	v_lshlrev_b32_e32 v30, 16, v31
	v_and_b32_e32 v31, 0xffff0000, v31
	v_lshlrev_b32_e32 v50, 16, v32
	v_and_b32_e32 v51, 0xffff0000, v32
	v_lshlrev_b32_e32 v58, 16, v40
	v_lshlrev_b32_e32 v60, 16, v42
	v_pk_mul_f32 v[62:63], v[46:47], v[46:47]
	v_pk_mul_f32 v[66:67], v[48:49], v[48:49]
	v_mov_b32_e32 v88, v59
	v_mov_b32_e32 v89, v61
	v_lshlrev_b32_e32 v32, 16, v33
	v_and_b32_e32 v33, 0xffff0000, v33
	v_lshlrev_b32_e32 v52, 16, v34
	v_and_b32_e32 v53, 0xffff0000, v34
	v_and_b32_e32 v55, 0xffff0000, v36
	v_and_b32_e32 v57, 0xffff0000, v38
	v_lshlrev_b32_e32 v40, 16, v41
	v_lshlrev_b32_e32 v42, 16, v43
	v_pk_mul_f32 v[64:65], v[28:29], v[28:29]
	v_pk_mul_f32 v[68:69], v[30:31], v[30:31]
	v_pk_mul_f32 v[70:71], v[50:51], v[50:51]
	v_mov_b32_e32 v86, v58
	v_mov_b32_e32 v87, v60
	v_pk_mul_f32 v[88:89], v[88:89], v[88:89]
	v_add_f32_e32 v94, v66, v67
	v_add_f32_e32 v95, v62, v63
	v_lshlrev_b32_e32 v34, 16, v35
	v_and_b32_e32 v35, 0xffff0000, v35
	v_lshlrev_b32_e32 v54, 16, v36
	v_lshlrev_b32_e32 v56, 16, v38
	v_and_b32_e32 v41, 0xffff0000, v41
	v_and_b32_e32 v43, 0xffff0000, v43
	v_pk_mul_f32 v[72:73], v[32:33], v[32:33]
	v_pk_mul_f32 v[74:75], v[52:53], v[52:53]
	v_mov_b32_e32 v80, v55
	v_mov_b32_e32 v81, v57
	v_mov_b32_e32 v90, v40
	v_mov_b32_e32 v91, v42
	v_add_f32_e32 v70, v70, v71
	v_pk_fma_f32 v[66:67], v[86:87], v[86:87], v[88:89]
	v_add_f32_e32 v68, v94, v68
	v_add_f32_e32 v64, v95, v64
	v_lshlrev_b32_e32 v36, 16, v37
	v_lshlrev_b32_e32 v38, 16, v39
	v_pk_mul_f32 v[76:77], v[34:35], v[34:35]
	v_mov_b32_e32 v78, v54
	v_mov_b32_e32 v79, v56
	v_mov_b32_e32 v92, v41
	v_mov_b32_e32 v93, v43
	v_pk_mul_f32 v[80:81], v[80:81], v[80:81]
	v_add_f32_e32 v71, v74, v75
	v_add_f32_e32 v70, v70, v72
	v_pk_fma_f32 v[66:67], v[90:91], v[90:91], v[66:67]
	v_add_f32_e32 v68, v69, v68
	v_add_f32_e32 v69, v65, v64
	v_and_b32_e32 v37, 0xffff0000, v37
	v_and_b32_e32 v39, 0xffff0000, v39
	v_mov_b32_e32 v82, v36
	v_mov_b32_e32 v83, v38
	v_pk_fma_f32 v[62:63], v[78:79], v[78:79], v[80:81]
	v_add_f32_e32 v71, v71, v76
	v_add_f32_e32 v70, v73, v70
	v_pk_fma_f32 v[64:65], v[92:93], v[92:93], v[66:67]
	v_add_f32_e32 v66, v69, v68
	v_mov_b32_e32 v84, v37
	v_mov_b32_e32 v85, v39
	v_pk_fma_f32 v[62:63], v[82:83], v[82:83], v[62:63]
	v_add_f32_e32 v71, v77, v71
	v_add_f32_e32 v66, v66, v70
	v_pk_fma_f32 v[62:63], v[84:85], v[84:85], v[62:63]
	v_add_f32_e32 v66, v66, v71
	v_add_f32_e32 v62, v66, v62
	v_add_f32_e32 v62, v62, v63
	v_add_f32_e32 v62, v62, v64
	v_add_f32_e32 v62, v62, v65
	ds_bpermute_b32 v63, v22, v62
	s_waitcnt lgkmcnt(0)
	v_add_f32_e32 v62, v62, v63
	ds_bpermute_b32 v63, v23, v62
	s_waitcnt lgkmcnt(0)
	v_add_f32_e32 v62, v62, v63
	ds_bpermute_b32 v63, v24, v62
	s_waitcnt lgkmcnt(0)
	v_add_f32_e32 v62, v62, v63
	ds_bpermute_b32 v63, v25, v62
	s_waitcnt lgkmcnt(0)
	v_add_f32_e32 v62, v62, v63
	ds_bpermute_b32 v63, v26, v62
	s_waitcnt lgkmcnt(0)
	v_add_f32_e32 v62, v62, v63
	ds_bpermute_b32 v63, v27, v62
	s_waitcnt lgkmcnt(0)
	v_add_f32_e32 v62, v62, v63
	v_fmamk_f32 v62, v62, 0x3a000000, v5
	v_mul_f32_e32 v63, 0x4b800000, v62
	v_cmp_gt_f32_e32 vcc, s1, v62
	s_nop 1
	v_cndmask_b32_e32 v62, v62, v63, vcc
	v_rsq_f32_e32 v62, v62
	s_nop 0
	v_mul_f32_e32 v63, 0x45800000, v62
	v_cndmask_b32_e32 v62, v62, v63, vcc
	v_pk_mul_f32 v[46:47], v[62:63], v[46:47] op_sel_hi:[0,1]
	v_pk_mul_f32 v[28:29], v[62:63], v[28:29] op_sel_hi:[0,1]
	v_pk_mul_f32 v[2:3], v[28:29], v[98:99]
	v_pk_mul_f32 v[0:1], v[46:47], v[96:97]
	global_store_dwordx4 v[44:45], v[0:3], off offset:-3072
	v_pk_mul_f32 v[28:29], v[62:63], v[30:31] op_sel_hi:[0,1]
	v_pk_mul_f32 v[30:31], v[62:63], v[48:49] op_sel_hi:[0,1]
	v_cmp_lt_i32_e32 vcc, s11, v7
	s_or_b64 s[8:9], vcc, s[8:9]
	v_pk_mul_f32 v[0:1], v[30:31], v[100:101]
	v_pk_mul_f32 v[2:3], v[28:29], v[102:103]
	global_store_dwordx4 v[44:45], v[0:3], off offset:-2048
	v_pk_mul_f32 v[28:29], v[62:63], v[32:33] op_sel_hi:[0,1]
	v_pk_mul_f32 v[30:31], v[62:63], v[50:51] op_sel_hi:[0,1]
	v_pk_mul_f32 v[0:1], v[30:31], v[104:105]
	v_pk_mul_f32 v[2:3], v[28:29], v[106:107]
	global_store_dwordx4 v[44:45], v[0:3], off offset:-1024
	v_pk_mul_f32 v[28:29], v[62:63], v[34:35] op_sel_hi:[0,1]
	v_pk_mul_f32 v[30:31], v[62:63], v[52:53] op_sel_hi:[0,1]
	v_pk_mul_f32 v[0:1], v[30:31], v[108:109]
	v_pk_mul_f32 v[2:3], v[28:29], v[110:111]
	global_store_dwordx4 v[20:21], v[0:3], off offset:-4096
	v_pk_mul_f32 v[28:29], v[62:63], v[54:55] op_sel_hi:[0,1]
	v_pk_mul_f32 v[30:31], v[62:63], v[36:37] op_sel_hi:[0,1]
	v_pk_mul_f32 v[0:1], v[28:29], v[112:113]
	v_pk_mul_f32 v[2:3], v[30:31], v[114:115]
	global_store_dwordx4 v[20:21], v[0:3], off offset:-3072
	v_pk_mul_f32 v[28:29], v[62:63], v[56:57] op_sel_hi:[0,1]
	v_pk_mul_f32 v[30:31], v[62:63], v[38:39] op_sel_hi:[0,1]
	v_pk_mul_f32 v[0:1], v[28:29], v[116:117]
	v_pk_mul_f32 v[2:3], v[30:31], v[118:119]
	global_store_dwordx4 v[20:21], v[0:3], off offset:-2048
	v_pk_mul_f32 v[28:29], v[62:63], v[58:59] op_sel_hi:[0,1]
	v_pk_mul_f32 v[30:31], v[62:63], v[40:41] op_sel_hi:[0,1]
	v_pk_mul_f32 v[0:1], v[28:29], v[120:121]
	v_pk_mul_f32 v[2:3], v[30:31], v[122:123]
	global_store_dwordx4 v[20:21], v[0:3], off offset:-1024
	v_pk_mul_f32 v[28:29], v[62:63], v[60:61] op_sel_hi:[0,1]
	v_pk_mul_f32 v[30:31], v[62:63], v[42:43] op_sel_hi:[0,1]
	v_pk_mul_f32 v[0:1], v[28:29], v[124:125]
	v_pk_mul_f32 v[2:3], v[30:31], v[126:127]
	global_store_dwordx4 v[20:21], v[0:3], off
	v_lshl_add_u64 v[20:21], v[20:21], 0, s[6:7]
	s_andn2_b64 exec, exec, s[8:9]
	s_cbranch_execnz .LBB0_1693
